# S5-out Toeplitz part re-ordered e-major: 7 LDS table fragments per 16 MFMAs instead of 16 (fragment depends on 16i-sI only), LDS reads one step ahead, same U-fragment ring
# speedup vs baseline: 1.0000x; 1.0000x over previous
; #define GAS __attribute__((address_space(1)))
; #define LAS __attribute__((address_space(3)))
; __device__ __forceinline__ v4u pack8(const float* x) { v4u w; w.x = pk2(x[0], x[1]); w.y = pk2(x[2], x[3]); w.z = pk2(x[4], x[5]); w.w = pk2(x[6], x[7]); return w; }
; __device__ __forceinline__ void ph_s5_out(Frame& F) {
;     ...
;     for (int u = F.vcu; u < 288; u += F.G) {
;         const int g = u / 9, nb = u % 9; int chunk = nb * 32 + r32; const bool valid = chunk < NCH; if (!valid) chunk = NCH - 1;
;         __syncthreads();
;         { const GAS v4u* tp = (const GAS v4u*)((const bf16*)(ws + WS_TOEP) + (size_t)g * 127 * 256); const float* t0 = (const float*)(ws + WS_T0) + (size_t)g * 512;
;           for (int c = tid; c < 127 * 32; c += 512) { const int di = c >> 5, p = (c >> 1) & 15, half = c & 1; v4u v;
;               if (di == 63) { float o[8];
; #pragma unroll
;                   for (int j = 0; j < 8; ++j) o[j] = t0[p * 16 + half * 8 + j] + t0[256 + p * 16 + half * 8 + j];
;                   v = pack8(o); }
;               else v = tp[c];
;               *(LAS v4u*)(L + (di * 16 + p) * TP_PITCH + half * 16) = v; } }
;         __syncthreads();
;         const bf16* ub = ug_frag_base(ws, g, nb, lane);
;         f32x16 acc[4];
; #pragma unroll
;         for (int i = 0; i < 4; ++i)
; #pragma unroll
;             for (int r = 0; r < 16; ++r) acc[i][r] = 0.f;
;         const LAS unsigned char* tl = L + ((63 + 2 * wave + (r32 >> 4)) * 16 + (r32 & 15)) * TP_PITCH + hh * 16;
; #pragma unroll 1
;         for (int s0 = 0; s0 < 64; s0 += 16) {
;             bf16x8_t bq[16];
; #pragma unroll
;             for (int e = 0; e < 16; ++e) bq[e] = *(const GAS bf16x8_t*)(ub + 512 * (s0 + e));
.LBB0_964:
	s_mul_hi_i32 s24, s48, 0x38e38e39
	s_lshr_b32 s25, s24, 31
	s_ashr_i32 s24, s24, 1
	s_add_i32 s26, s24, s25
	s_ashr_i32 s27, s26, 31
	s_mul_i32 s28, s26, 9
	s_sub_i32 s28, s48, s28
	s_lshl_b32 s29, s26, 3
	s_add_i32 s29, s29, s28
	s_cmp_lt_i32 s28, 8
	s_cselect_b32 s28, s29, s26
	s_cselect_b32 s34, s41, 0xdc00000
	s_ashr_i32 s29, s28, 31
	s_lshl_b64 s[28:29], s[28:29], 16
	s_add_u32 s28, s34, s28
	s_addc_u32 s29, 0, s29
	v_lshl_add_u64 v[82:83], v[76:77], 0, s[28:29]
	v_add_co_u32_e32 v140, vcc, 0xffffd400, v82
	s_nop 1
	v_addc_co_u32_e32 v141, vcc, -1, v83, vcc
	v_lshl_add_u64 v[210:211], v[140:141], 0, s[22:23]
	v_lshl_add_u64 v[212:213], v[210:211], 0, s[22:23]
	v_lshl_add_u64 v[88:89], v[212:213], 0, s[22:23]
	global_load_dwordx4 v[142:145], v[140:141], off offset:-4096
	global_load_dwordx4 v[146:149], v[210:211], off offset:-4096
	global_load_dwordx4 v[150:153], v[212:213], off offset:-4096
	global_load_dwordx4 v[154:157], v[88:89], off offset:-4096
	global_load_dwordx4 v[158:161], v[140:141], off offset:-3072
	global_load_dwordx4 v[162:165], v[210:211], off offset:-3072
	global_load_dwordx4 v[166:169], v[212:213], off offset:-3072
	global_load_dwordx4 v[170:173], v[88:89], off offset:-3072
	global_load_dwordx4 v[174:177], v[140:141], off offset:-2048
	global_load_dwordx4 v[178:181], v[210:211], off offset:-2048
	global_load_dwordx4 v[182:185], v[212:213], off offset:-2048
	global_load_dwordx4 v[190:193], v[88:89], off offset:-2048
	global_load_dwordx4 v[194:197], v[140:141], off offset:-1024
	global_load_dwordx4 v[198:201], v[210:211], off offset:-1024
	global_load_dwordx4 v[202:205], v[212:213], off offset:-1024
	global_load_dwordx4 v[206:209], v[88:89], off offset:-1024
	s_barrier
	s_and_saveexec_b64 s[24:25], s[2:3]
	s_cbranch_execz .LBB0_971
	s_lshl_b64 s[28:29], s[26:27], 11
	s_add_u32 s28, s36, s28
	v_mad_i64_i32 v[6:7], s[30:31], s26, v93, v[74:75]
	s_addc_u32 s29, s37, s29
	v_lshrrev_b32_e32 v216, 5, v236
	v_bfe_u32 v10, v236, 1, 4
	v_lshl_or_b32 v216, v216, 4, v10
	v_mad_u32_u24 v216, v216, 48, v72
	v_add_u32_e32 v217, 0xc000, v216
	global_load_dwordx4 v[96:99], v[6:7], off
	v_lshl_add_u64 v[214:215], v[6:7], 0, s[20:21]
	global_load_dwordx4 v[100:103], v[214:215], off
	v_lshl_add_u64 v[214:215], v[214:215], 0, s[20:21]
	global_load_dwordx4 v[104:107], v[214:215], off
	v_lshl_add_u64 v[214:215], v[214:215], 0, s[20:21]
	global_load_dwordx4 v[108:111], v[214:215], off
	v_lshl_add_u64 v[214:215], v[214:215], 0, s[20:21]
	global_load_dwordx4 v[112:115], v[214:215], off
	v_lshl_add_u64 v[214:215], v[214:215], 0, s[20:21]
	global_load_dwordx4 v[116:119], v[214:215], off
	v_lshl_add_u64 v[214:215], v[214:215], 0, s[20:21]
	global_load_dwordx4 v[120:123], v[214:215], off
	v_lshl_add_u64 v[214:215], v[214:215], 0, s[20:21]
	v_cmp_gt_u32_e32 vcc, 0x1e0, v236
	s_and_saveexec_b64 s[30:31], vcc
	global_load_dwordx4 v[124:127], v[214:215], off
	s_andn2_b64 exec, s[30:31], exec
	s_cbranch_execz .Ls5_t0_done
	v_lshl_or_b32 v11, v10, 6, v92
	global_load_dwordx4 v[128:131], v11, s[28:29] offset:1024
	global_load_dwordx4 v[132:135], v11, s[28:29]
	global_load_dwordx4 v[20:23], v11, s[28:29] offset:16
	global_load_dwordx4 v[24:27], v11, s[28:29] offset:1040
	s_waitcnt vmcnt(0)
	v_pk_add_f32 v[128:129], v[132:133], v[128:129]
	v_pk_add_f32 v[130:131], v[134:135], v[130:131]
	v_pk_add_f32 v[132:133], v[20:21], v[24:25]
	v_pk_add_f32 v[134:135], v[22:23], v[26:27]
	v_cvt_pk_bf16_f32 v108, v128, v129
	v_cvt_pk_bf16_f32 v109, v130, v131
	v_cvt_pk_bf16_f32 v110, v132, v133
	v_cvt_pk_bf16_f32 v111, v134, v135

; #define GAS __attribute__((address_space(1)))
; #define LAS __attribute__((address_space(3)))
; __device__ __forceinline__ void ph_s5_out(Frame& F) {
;     ...
;         const LAS unsigned char* tl = L + ((63 + 2 * wave + (r32 >> 4)) * 16 + (r32 & 15)) * TP_PITCH + hh * 16;
; #pragma unroll 1
;         for (int s0 = 0; s0 < 64; s0 += 16) {
;             bf16x8_t bq[16];
; #pragma unroll
;             for (int e = 0; e < 16; ++e) bq[e] = *(const GAS bf16x8_t*)(ub + 512 * (s0 + e));
; #pragma unroll
;             for (int e = 0; e < 16; ++e) { const int sI = s0 + e; const bf16x8_t b = bq[e];
; #pragma unroll
;             for (int i = 0; i < 4; ++i) { const bf16x8_t a = *(const LAS bf16x8_t*)(tl + (16 * i - sI) * 16 * TP_PITCH); acc[i] = __builtin_amdgcn_mfma_f32_32x32x16_bf16(a, b, acc[i], 0, 0, 0); }
;             }
.LBB0_972:
	v_add_u32_e32 v68, 0xffff7000, v91
	ds_read_b128 v[84:87], v68 offset:11520
	ds_read_b128 v[96:99], v68 offset:23808
	ds_read_b128 v[100:103], v68 offset:36096
	ds_read_b128 v[104:107], v91 offset:11520
	ds_read_b128 v[108:111], v91 offset:23808
	ds_read_b128 v[112:115], v91 offset:36096
	ds_read_b128 v[116:119], v91 offset:48384
	ds_read_b128 v[120:123], v68 offset:10752
	ds_read_b128 v[124:127], v68 offset:23040
	ds_read_b128 v[128:131], v68 offset:35328
	ds_read_b128 v[132:135], v91 offset:10752
	ds_read_b128 v[136:139], v91 offset:23040
	ds_read_b128 v[218:221], v91 offset:35328
	ds_read_b128 v[222:225], v91 offset:47616
	s_waitcnt vmcnt(15) lgkmcnt(7)
	v_mfma_f32_32x32x16_bf16 v[50:65], v[104:107], v[142:145], v[50:65]
	v_mfma_f32_32x32x16_bf16 v[34:49], v[108:111], v[142:145], v[34:49]
	v_mfma_f32_32x32x16_bf16 v[18:33], v[112:115], v[142:145], v[18:33]
	v_mfma_f32_32x32x16_bf16 v[2:17], v[116:119], v[142:145], v[2:17]
	global_load_dwordx4 v[142:145], v[140:141], off
	s_waitcnt vmcnt(15)
	v_mfma_f32_32x32x16_bf16 v[50:65], v[100:103], v[146:149], v[50:65]
	v_mfma_f32_32x32x16_bf16 v[34:49], v[104:107], v[146:149], v[34:49]
	v_mfma_f32_32x32x16_bf16 v[18:33], v[108:111], v[146:149], v[18:33]
	v_mfma_f32_32x32x16_bf16 v[2:17], v[112:115], v[146:149], v[2:17]
	global_load_dwordx4 v[146:149], v[210:211], off
	s_waitcnt vmcnt(15)
	v_mfma_f32_32x32x16_bf16 v[50:65], v[96:99], v[150:153], v[50:65]
	v_mfma_f32_32x32x16_bf16 v[34:49], v[100:103], v[150:153], v[34:49]
	v_mfma_f32_32x32x16_bf16 v[18:33], v[104:107], v[150:153], v[18:33]
	v_mfma_f32_32x32x16_bf16 v[2:17], v[108:111], v[150:153], v[2:17]
	global_load_dwordx4 v[150:153], v[212:213], off
	s_waitcnt vmcnt(15)
	v_mfma_f32_32x32x16_bf16 v[50:65], v[84:87], v[154:157], v[50:65]
	v_mfma_f32_32x32x16_bf16 v[34:49], v[96:99], v[154:157], v[34:49]
	v_mfma_f32_32x32x16_bf16 v[18:33], v[100:103], v[154:157], v[18:33]
	v_mfma_f32_32x32x16_bf16 v[2:17], v[104:107], v[154:157], v[2:17]
	global_load_dwordx4 v[154:157], v[88:89], off
	ds_read_b128 v[84:87], v68 offset:9984
	ds_read_b128 v[96:99], v68 offset:22272
	ds_read_b128 v[100:103], v68 offset:34560
	ds_read_b128 v[104:107], v91 offset:9984
	ds_read_b128 v[108:111], v91 offset:22272
	ds_read_b128 v[112:115], v91 offset:34560
	ds_read_b128 v[116:119], v91 offset:46848
	s_waitcnt vmcnt(15) lgkmcnt(7)
	v_mfma_f32_32x32x16_bf16 v[50:65], v[132:135], v[158:161], v[50:65]
	v_mfma_f32_32x32x16_bf16 v[34:49], v[136:139], v[158:161], v[34:49]
	v_mfma_f32_32x32x16_bf16 v[18:33], v[218:221], v[158:161], v[18:33]
	v_mfma_f32_32x32x16_bf16 v[2:17], v[222:225], v[158:161], v[2:17]
	global_load_dwordx4 v[158:161], v[140:141], off offset:1024
	s_waitcnt vmcnt(15)
	v_mfma_f32_32x32x16_bf16 v[50:65], v[128:131], v[162:165], v[50:65]
	v_mfma_f32_32x32x16_bf16 v[34:49], v[132:135], v[162:165], v[34:49]
	v_mfma_f32_32x32x16_bf16 v[18:33], v[136:139], v[162:165], v[18:33]
	v_mfma_f32_32x32x16_bf16 v[2:17], v[218:221], v[162:165], v[2:17]
	global_load_dwordx4 v[162:165], v[210:211], off offset:1024
	s_waitcnt vmcnt(15)
	v_mfma_f32_32x32x16_bf16 v[50:65], v[124:127], v[166:169], v[50:65]
	v_mfma_f32_32x32x16_bf16 v[34:49], v[128:131], v[166:169], v[34:49]
	v_mfma_f32_32x32x16_bf16 v[18:33], v[132:135], v[166:169], v[18:33]
	v_mfma_f32_32x32x16_bf16 v[2:17], v[136:139], v[166:169], v[2:17]
	global_load_dwordx4 v[166:169], v[212:213], off offset:1024
	s_waitcnt vmcnt(15)
	v_mfma_f32_32x32x16_bf16 v[50:65], v[120:123], v[170:173], v[50:65]
	v_mfma_f32_32x32x16_bf16 v[34:49], v[124:127], v[170:173], v[34:49]
	v_mfma_f32_32x32x16_bf16 v[18:33], v[128:131], v[170:173], v[18:33]
	v_mfma_f32_32x32x16_bf16 v[2:17], v[132:135], v[170:173], v[2:17]
	global_load_dwordx4 v[170:173], v[88:89], off offset:1024
	ds_read_b128 v[120:123], v68 offset:9216
	ds_read_b128 v[124:127], v68 offset:21504
	ds_read_b128 v[128:131], v68 offset:33792
	ds_read_b128 v[132:135], v91 offset:9216
	ds_read_b128 v[136:139], v91 offset:21504
	ds_read_b128 v[218:221], v91 offset:33792
	ds_read_b128 v[222:225], v91 offset:46080
	s_waitcnt vmcnt(15) lgkmcnt(7)
	v_mfma_f32_32x32x16_bf16 v[50:65], v[104:107], v[174:177], v[50:65]
	v_mfma_f32_32x32x16_bf16 v[34:49], v[108:111], v[174:177], v[34:49]
	v_mfma_f32_32x32x16_bf16 v[18:33], v[112:115], v[174:177], v[18:33]
	v_mfma_f32_32x32x16_bf16 v[2:17], v[116:119], v[174:177], v[2:17]
	global_load_dwordx4 v[174:177], v[140:141], off offset:2048
	s_waitcnt vmcnt(15)
	v_mfma_f32_32x32x16_bf16 v[50:65], v[100:103], v[178:181], v[50:65]
	v_mfma_f32_32x32x16_bf16 v[34:49], v[104:107], v[178:181], v[34:49]
	v_mfma_f32_32x32x16_bf16 v[18:33], v[108:111], v[178:181], v[18:33]
	v_mfma_f32_32x32x16_bf16 v[2:17], v[112:115], v[178:181], v[2:17]
	global_load_dwordx4 v[178:181], v[210:211], off offset:2048
	s_waitcnt vmcnt(15)
	v_mfma_f32_32x32x16_bf16 v[50:65], v[96:99], v[182:185], v[50:65]
	v_mfma_f32_32x32x16_bf16 v[34:49], v[100:103], v[182:185], v[34:49]
	v_mfma_f32_32x32x16_bf16 v[18:33], v[104:107], v[182:185], v[18:33]
	v_mfma_f32_32x32x16_bf16 v[2:17], v[108:111], v[182:185], v[2:17]
	global_load_dwordx4 v[182:185], v[212:213], off offset:2048
	s_waitcnt vmcnt(15)
	v_mfma_f32_32x32x16_bf16 v[50:65], v[84:87], v[190:193], v[50:65]
	v_mfma_f32_32x32x16_bf16 v[34:49], v[96:99], v[190:193], v[34:49]
	v_mfma_f32_32x32x16_bf16 v[18:33], v[100:103], v[190:193], v[18:33]
	v_mfma_f32_32x32x16_bf16 v[2:17], v[104:107], v[190:193], v[2:17]
	global_load_dwordx4 v[190:193], v[88:89], off offset:2048
	ds_read_b128 v[84:87], v68 offset:8448
	ds_read_b128 v[96:99], v68 offset:20736
	ds_read_b128 v[100:103], v68 offset:33024
	ds_read_b128 v[104:107], v91 offset:8448
	ds_read_b128 v[108:111], v91 offset:20736
	ds_read_b128 v[112:115], v91 offset:33024
	ds_read_b128 v[116:119], v91 offset:45312
	s_waitcnt vmcnt(15) lgkmcnt(7)
; #define GAS __attribute__((address_space(1)))
; #define LAS __attribute__((address_space(3)))
; __device__ __forceinline__ void ph_s5_out(Frame& F) {
;     ...
;         const LAS unsigned char* tl = L + ((63 + 2 * wave + (r32 >> 4)) * 16 + (r32 & 15)) * TP_PITCH + hh * 16;
; #pragma unroll 1
;         for (int s0 = 0; s0 < 64; s0 += 16) {
;             bf16x8_t bq[16];
; #pragma unroll
;             for (int e = 0; e < 16; ++e) bq[e] = *(const GAS bf16x8_t*)(ub + 512 * (s0 + e));
; #pragma unroll
;             for (int e = 0; e < 16; ++e) { const int sI = s0 + e; const bf16x8_t b = bq[e];
; #pragma unroll
;             for (int i = 0; i < 4; ++i) { const bf16x8_t a = *(const LAS bf16x8_t*)(tl + (16 * i - sI) * 16 * TP_PITCH); acc[i] = __builtin_amdgcn_mfma_f32_32x32x16_bf16(a, b, acc[i], 0, 0, 0); }
;             }
	v_mfma_f32_32x32x16_bf16 v[50:65], v[132:135], v[194:197], v[50:65]
	v_mfma_f32_32x32x16_bf16 v[34:49], v[136:139], v[194:197], v[34:49]
	v_mfma_f32_32x32x16_bf16 v[18:33], v[218:221], v[194:197], v[18:33]
	v_mfma_f32_32x32x16_bf16 v[2:17], v[222:225], v[194:197], v[2:17]
	global_load_dwordx4 v[194:197], v[140:141], off offset:3072
	s_waitcnt vmcnt(15)
	v_mfma_f32_32x32x16_bf16 v[50:65], v[128:131], v[198:201], v[50:65]
	v_mfma_f32_32x32x16_bf16 v[34:49], v[132:135], v[198:201], v[34:49]
	v_mfma_f32_32x32x16_bf16 v[18:33], v[136:139], v[198:201], v[18:33]
	v_mfma_f32_32x32x16_bf16 v[2:17], v[218:221], v[198:201], v[2:17]
	global_load_dwordx4 v[198:201], v[210:211], off offset:3072
	s_waitcnt vmcnt(15)
	v_mfma_f32_32x32x16_bf16 v[50:65], v[124:127], v[202:205], v[50:65]
	v_mfma_f32_32x32x16_bf16 v[34:49], v[128:131], v[202:205], v[34:49]
	v_mfma_f32_32x32x16_bf16 v[18:33], v[132:135], v[202:205], v[18:33]
	v_mfma_f32_32x32x16_bf16 v[2:17], v[136:139], v[202:205], v[2:17]
	global_load_dwordx4 v[202:205], v[212:213], off offset:3072
	s_waitcnt vmcnt(15)
	v_mfma_f32_32x32x16_bf16 v[50:65], v[120:123], v[206:209], v[50:65]
	v_mfma_f32_32x32x16_bf16 v[34:49], v[124:127], v[206:209], v[34:49]
	v_mfma_f32_32x32x16_bf16 v[18:33], v[128:131], v[206:209], v[18:33]
	v_mfma_f32_32x32x16_bf16 v[2:17], v[132:135], v[206:209], v[2:17]
	global_load_dwordx4 v[206:209], v[88:89], off offset:3072
	v_lshl_add_u64 v[140:141], v[140:141], 0, s[20:21]
	v_lshl_add_u64 v[210:211], v[210:211], 0, s[20:21]
	v_lshl_add_u64 v[212:213], v[212:213], 0, s[20:21]
	v_lshl_add_u64 v[88:89], v[88:89], 0, s[20:21]
	ds_read_b128 v[120:123], v68 offset:7680
	ds_read_b128 v[124:127], v68 offset:19968
	ds_read_b128 v[128:131], v68 offset:32256
	ds_read_b128 v[132:135], v91 offset:7680
	ds_read_b128 v[136:139], v91 offset:19968
	ds_read_b128 v[218:221], v91 offset:32256
	ds_read_b128 v[222:225], v91 offset:44544
	s_waitcnt vmcnt(15) lgkmcnt(7)
	v_mfma_f32_32x32x16_bf16 v[50:65], v[104:107], v[142:145], v[50:65]
	v_mfma_f32_32x32x16_bf16 v[34:49], v[108:111], v[142:145], v[34:49]
	v_mfma_f32_32x32x16_bf16 v[18:33], v[112:115], v[142:145], v[18:33]
	v_mfma_f32_32x32x16_bf16 v[2:17], v[116:119], v[142:145], v[2:17]
	global_load_dwordx4 v[142:145], v[140:141], off offset:-4096
	s_waitcnt vmcnt(15)
	v_mfma_f32_32x32x16_bf16 v[50:65], v[100:103], v[146:149], v[50:65]
	v_mfma_f32_32x32x16_bf16 v[34:49], v[104:107], v[146:149], v[34:49]
	v_mfma_f32_32x32x16_bf16 v[18:33], v[108:111], v[146:149], v[18:33]
	v_mfma_f32_32x32x16_bf16 v[2:17], v[112:115], v[146:149], v[2:17]
	global_load_dwordx4 v[146:149], v[210:211], off offset:-4096
	s_waitcnt vmcnt(15)
	v_mfma_f32_32x32x16_bf16 v[50:65], v[96:99], v[150:153], v[50:65]
	v_mfma_f32_32x32x16_bf16 v[34:49], v[100:103], v[150:153], v[34:49]
	v_mfma_f32_32x32x16_bf16 v[18:33], v[104:107], v[150:153], v[18:33]
	v_mfma_f32_32x32x16_bf16 v[2:17], v[108:111], v[150:153], v[2:17]
	global_load_dwordx4 v[150:153], v[212:213], off offset:-4096
	s_waitcnt vmcnt(15)
	v_mfma_f32_32x32x16_bf16 v[50:65], v[84:87], v[154:157], v[50:65]
	v_mfma_f32_32x32x16_bf16 v[34:49], v[96:99], v[154:157], v[34:49]
	v_mfma_f32_32x32x16_bf16 v[18:33], v[100:103], v[154:157], v[18:33]
	v_mfma_f32_32x32x16_bf16 v[2:17], v[104:107], v[154:157], v[2:17]
	global_load_dwordx4 v[154:157], v[88:89], off offset:-4096
	ds_read_b128 v[84:87], v68 offset:6912
	ds_read_b128 v[96:99], v68 offset:19200
	ds_read_b128 v[100:103], v68 offset:31488
	ds_read_b128 v[104:107], v91 offset:6912
	ds_read_b128 v[108:111], v91 offset:19200
	ds_read_b128 v[112:115], v91 offset:31488
	ds_read_b128 v[116:119], v91 offset:43776
	s_waitcnt vmcnt(15) lgkmcnt(7)
	v_mfma_f32_32x32x16_bf16 v[50:65], v[132:135], v[158:161], v[50:65]
	v_mfma_f32_32x32x16_bf16 v[34:49], v[136:139], v[158:161], v[34:49]
	v_mfma_f32_32x32x16_bf16 v[18:33], v[218:221], v[158:161], v[18:33]
	v_mfma_f32_32x32x16_bf16 v[2:17], v[222:225], v[158:161], v[2:17]
	global_load_dwordx4 v[158:161], v[140:141], off offset:-3072
	s_waitcnt vmcnt(15)
	v_mfma_f32_32x32x16_bf16 v[50:65], v[128:131], v[162:165], v[50:65]
	v_mfma_f32_32x32x16_bf16 v[34:49], v[132:135], v[162:165], v[34:49]
	v_mfma_f32_32x32x16_bf16 v[18:33], v[136:139], v[162:165], v[18:33]
	v_mfma_f32_32x32x16_bf16 v[2:17], v[218:221], v[162:165], v[2:17]
	global_load_dwordx4 v[162:165], v[210:211], off offset:-3072
	s_waitcnt vmcnt(15)
	v_mfma_f32_32x32x16_bf16 v[50:65], v[124:127], v[166:169], v[50:65]
	v_mfma_f32_32x32x16_bf16 v[34:49], v[128:131], v[166:169], v[34:49]
	v_mfma_f32_32x32x16_bf16 v[18:33], v[132:135], v[166:169], v[18:33]
	v_mfma_f32_32x32x16_bf16 v[2:17], v[136:139], v[166:169], v[2:17]
	global_load_dwordx4 v[166:169], v[212:213], off offset:-3072
	s_waitcnt vmcnt(15)
	v_mfma_f32_32x32x16_bf16 v[50:65], v[120:123], v[170:173], v[50:65]
	v_mfma_f32_32x32x16_bf16 v[34:49], v[124:127], v[170:173], v[34:49]
	v_mfma_f32_32x32x16_bf16 v[18:33], v[128:131], v[170:173], v[18:33]
	v_mfma_f32_32x32x16_bf16 v[2:17], v[132:135], v[170:173], v[2:17]
	global_load_dwordx4 v[170:173], v[88:89], off offset:-3072
	ds_read_b128 v[120:123], v68 offset:6144
	ds_read_b128 v[124:127], v68 offset:18432
	ds_read_b128 v[128:131], v68 offset:30720
	ds_read_b128 v[132:135], v91 offset:6144
	ds_read_b128 v[136:139], v91 offset:18432
	ds_read_b128 v[218:221], v91 offset:30720
	ds_read_b128 v[222:225], v91 offset:43008
	s_waitcnt vmcnt(15) lgkmcnt(7)
	v_mfma_f32_32x32x16_bf16 v[50:65], v[104:107], v[174:177], v[50:65]
	v_mfma_f32_32x32x16_bf16 v[34:49], v[108:111], v[174:177], v[34:49]
	v_mfma_f32_32x32x16_bf16 v[18:33], v[112:115], v[174:177], v[18:33]
	v_mfma_f32_32x32x16_bf16 v[2:17], v[116:119], v[174:177], v[2:17]
	global_load_dwordx4 v[174:177], v[140:141], off offset:-2048
	s_waitcnt vmcnt(15)
; #define GAS __attribute__((address_space(1)))
; #define LAS __attribute__((address_space(3)))
; __device__ __forceinline__ void ph_s5_out(Frame& F) {
;     ...
;         const LAS unsigned char* tl = L + ((63 + 2 * wave + (r32 >> 4)) * 16 + (r32 & 15)) * TP_PITCH + hh * 16;
; #pragma unroll 1
;         for (int s0 = 0; s0 < 64; s0 += 16) {
;             bf16x8_t bq[16];
; #pragma unroll
;             for (int e = 0; e < 16; ++e) bq[e] = *(const GAS bf16x8_t*)(ub + 512 * (s0 + e));
; #pragma unroll
;             for (int e = 0; e < 16; ++e) { const int sI = s0 + e; const bf16x8_t b = bq[e];
; #pragma unroll
;             for (int i = 0; i < 4; ++i) { const bf16x8_t a = *(const LAS bf16x8_t*)(tl + (16 * i - sI) * 16 * TP_PITCH); acc[i] = __builtin_amdgcn_mfma_f32_32x32x16_bf16(a, b, acc[i], 0, 0, 0); }
;             }
	v_mfma_f32_32x32x16_bf16 v[50:65], v[100:103], v[178:181], v[50:65]
	v_mfma_f32_32x32x16_bf16 v[34:49], v[104:107], v[178:181], v[34:49]
	v_mfma_f32_32x32x16_bf16 v[18:33], v[108:111], v[178:181], v[18:33]
	v_mfma_f32_32x32x16_bf16 v[2:17], v[112:115], v[178:181], v[2:17]
	global_load_dwordx4 v[178:181], v[210:211], off offset:-2048
	s_waitcnt vmcnt(15)
	v_mfma_f32_32x32x16_bf16 v[50:65], v[96:99], v[182:185], v[50:65]
	v_mfma_f32_32x32x16_bf16 v[34:49], v[100:103], v[182:185], v[34:49]
	v_mfma_f32_32x32x16_bf16 v[18:33], v[104:107], v[182:185], v[18:33]
	v_mfma_f32_32x32x16_bf16 v[2:17], v[108:111], v[182:185], v[2:17]
	global_load_dwordx4 v[182:185], v[212:213], off offset:-2048
	s_waitcnt vmcnt(15)
	v_mfma_f32_32x32x16_bf16 v[50:65], v[84:87], v[190:193], v[50:65]
	v_mfma_f32_32x32x16_bf16 v[34:49], v[96:99], v[190:193], v[34:49]
	v_mfma_f32_32x32x16_bf16 v[18:33], v[100:103], v[190:193], v[18:33]
	v_mfma_f32_32x32x16_bf16 v[2:17], v[104:107], v[190:193], v[2:17]
	global_load_dwordx4 v[190:193], v[88:89], off offset:-2048
	ds_read_b128 v[84:87], v68 offset:5376
	ds_read_b128 v[96:99], v68 offset:17664
	ds_read_b128 v[100:103], v68 offset:29952
	ds_read_b128 v[104:107], v91 offset:5376
	ds_read_b128 v[108:111], v91 offset:17664
	ds_read_b128 v[112:115], v91 offset:29952
	ds_read_b128 v[116:119], v91 offset:42240
	s_waitcnt vmcnt(15) lgkmcnt(7)
	v_mfma_f32_32x32x16_bf16 v[50:65], v[132:135], v[194:197], v[50:65]
	v_mfma_f32_32x32x16_bf16 v[34:49], v[136:139], v[194:197], v[34:49]
	v_mfma_f32_32x32x16_bf16 v[18:33], v[218:221], v[194:197], v[18:33]
	v_mfma_f32_32x32x16_bf16 v[2:17], v[222:225], v[194:197], v[2:17]
	global_load_dwordx4 v[194:197], v[140:141], off offset:-1024
	s_waitcnt vmcnt(15)
	v_mfma_f32_32x32x16_bf16 v[50:65], v[128:131], v[198:201], v[50:65]
	v_mfma_f32_32x32x16_bf16 v[34:49], v[132:135], v[198:201], v[34:49]
	v_mfma_f32_32x32x16_bf16 v[18:33], v[136:139], v[198:201], v[18:33]
	v_mfma_f32_32x32x16_bf16 v[2:17], v[218:221], v[198:201], v[2:17]
	global_load_dwordx4 v[198:201], v[210:211], off offset:-1024
	s_waitcnt vmcnt(15)
	v_mfma_f32_32x32x16_bf16 v[50:65], v[124:127], v[202:205], v[50:65]
	v_mfma_f32_32x32x16_bf16 v[34:49], v[128:131], v[202:205], v[34:49]
	v_mfma_f32_32x32x16_bf16 v[18:33], v[132:135], v[202:205], v[18:33]
	v_mfma_f32_32x32x16_bf16 v[2:17], v[136:139], v[202:205], v[2:17]
	global_load_dwordx4 v[202:205], v[212:213], off offset:-1024
	s_waitcnt vmcnt(15)
	v_mfma_f32_32x32x16_bf16 v[50:65], v[120:123], v[206:209], v[50:65]
	v_mfma_f32_32x32x16_bf16 v[34:49], v[124:127], v[206:209], v[34:49]
	v_mfma_f32_32x32x16_bf16 v[18:33], v[128:131], v[206:209], v[18:33]
	v_mfma_f32_32x32x16_bf16 v[2:17], v[132:135], v[206:209], v[2:17]
	global_load_dwordx4 v[206:209], v[88:89], off offset:-1024
	ds_read_b128 v[120:123], v68 offset:4608
	ds_read_b128 v[124:127], v68 offset:16896
	ds_read_b128 v[128:131], v68 offset:29184
	ds_read_b128 v[132:135], v91 offset:4608
	ds_read_b128 v[136:139], v91 offset:16896
	ds_read_b128 v[218:221], v91 offset:29184
	ds_read_b128 v[222:225], v91 offset:41472
	s_waitcnt vmcnt(15) lgkmcnt(7)
	v_mfma_f32_32x32x16_bf16 v[50:65], v[104:107], v[142:145], v[50:65]
	v_mfma_f32_32x32x16_bf16 v[34:49], v[108:111], v[142:145], v[34:49]
	v_mfma_f32_32x32x16_bf16 v[18:33], v[112:115], v[142:145], v[18:33]
	v_mfma_f32_32x32x16_bf16 v[2:17], v[116:119], v[142:145], v[2:17]
	global_load_dwordx4 v[142:145], v[140:141], off
	s_waitcnt vmcnt(15)
	v_mfma_f32_32x32x16_bf16 v[50:65], v[100:103], v[146:149], v[50:65]
	v_mfma_f32_32x32x16_bf16 v[34:49], v[104:107], v[146:149], v[34:49]
	v_mfma_f32_32x32x16_bf16 v[18:33], v[108:111], v[146:149], v[18:33]
	v_mfma_f32_32x32x16_bf16 v[2:17], v[112:115], v[146:149], v[2:17]
	global_load_dwordx4 v[146:149], v[210:211], off
	s_waitcnt vmcnt(15)
	v_mfma_f32_32x32x16_bf16 v[50:65], v[96:99], v[150:153], v[50:65]
	v_mfma_f32_32x32x16_bf16 v[34:49], v[100:103], v[150:153], v[34:49]
	v_mfma_f32_32x32x16_bf16 v[18:33], v[104:107], v[150:153], v[18:33]
	v_mfma_f32_32x32x16_bf16 v[2:17], v[108:111], v[150:153], v[2:17]
	global_load_dwordx4 v[150:153], v[212:213], off
	s_waitcnt vmcnt(15)
	v_mfma_f32_32x32x16_bf16 v[50:65], v[84:87], v[154:157], v[50:65]
	v_mfma_f32_32x32x16_bf16 v[34:49], v[96:99], v[154:157], v[34:49]
	v_mfma_f32_32x32x16_bf16 v[18:33], v[100:103], v[154:157], v[18:33]
	v_mfma_f32_32x32x16_bf16 v[2:17], v[104:107], v[154:157], v[2:17]
	global_load_dwordx4 v[154:157], v[88:89], off
	ds_read_b128 v[84:87], v68 offset:3840
	ds_read_b128 v[96:99], v68 offset:16128
	ds_read_b128 v[100:103], v68 offset:28416
	ds_read_b128 v[104:107], v91 offset:3840
	ds_read_b128 v[108:111], v91 offset:16128
	ds_read_b128 v[112:115], v91 offset:28416
	ds_read_b128 v[116:119], v91 offset:40704
	s_waitcnt vmcnt(15) lgkmcnt(7)
	v_mfma_f32_32x32x16_bf16 v[50:65], v[132:135], v[158:161], v[50:65]
	v_mfma_f32_32x32x16_bf16 v[34:49], v[136:139], v[158:161], v[34:49]
	v_mfma_f32_32x32x16_bf16 v[18:33], v[218:221], v[158:161], v[18:33]
	v_mfma_f32_32x32x16_bf16 v[2:17], v[222:225], v[158:161], v[2:17]
	global_load_dwordx4 v[158:161], v[140:141], off offset:1024
	s_waitcnt vmcnt(15)
	v_mfma_f32_32x32x16_bf16 v[50:65], v[128:131], v[162:165], v[50:65]
	v_mfma_f32_32x32x16_bf16 v[34:49], v[132:135], v[162:165], v[34:49]
	v_mfma_f32_32x32x16_bf16 v[18:33], v[136:139], v[162:165], v[18:33]
	v_mfma_f32_32x32x16_bf16 v[2:17], v[218:221], v[162:165], v[2:17]
	global_load_dwordx4 v[162:165], v[210:211], off offset:1024
	s_waitcnt vmcnt(15)
; #define GAS __attribute__((address_space(1)))
; #define LAS __attribute__((address_space(3)))
; __device__ __forceinline__ void ph_s5_out(Frame& F) {
;     ...
;         for (int s0 = 0; s0 < 64; s0 += 16) {
;             bf16x8_t bq[16];
; #pragma unroll
;             for (int e = 0; e < 16; ++e) bq[e] = *(const GAS bf16x8_t*)(ub + 512 * (s0 + e));
; #pragma unroll
;             for (int e = 0; e < 16; ++e) { const int sI = s0 + e; const bf16x8_t b = bq[e];
; #pragma unroll
;             for (int i = 0; i < 4; ++i) { const bf16x8_t a = *(const LAS bf16x8_t*)(tl + (16 * i - sI) * 16 * TP_PITCH); acc[i] = __builtin_amdgcn_mfma_f32_32x32x16_bf16(a, b, acc[i], 0, 0, 0); }
;             }
;         }
;         { const bf16* sb = (const bf16*)(ws + WS_SIN) + (size_t)g * 9 * 16 * 512 + ((size_t)nb * 16 * 64 + lane) * 8;
;           const bf16* wc = (const bf16*)(ws + WS_WC) + (size_t)g * 1024 * 256 + (((size_t)wave * 16) * 64 + lane) * 8;
; #pragma unroll 4
;           for (int kk = 0; kk < 16; ++kk) {
;               const bf16x8_t b = *(const GAS bf16x8_t*)(sb + 512 * kk);
; #pragma unroll
;               for (int i = 0; i < 4; ++i) { const bf16x8_t a = *(const GAS bf16x8_t*)(wc + (size_t)(8 * i) * 16 * 512 + 512 * kk); acc[i] = __builtin_amdgcn_mfma_f32_32x32x16_bf16(a, b, acc[i], 0, 0, 0); }
;           } }
	v_mfma_f32_32x32x16_bf16 v[50:65], v[124:127], v[166:169], v[50:65]
	v_mfma_f32_32x32x16_bf16 v[34:49], v[128:131], v[166:169], v[34:49]
	v_mfma_f32_32x32x16_bf16 v[18:33], v[132:135], v[166:169], v[18:33]
	v_mfma_f32_32x32x16_bf16 v[2:17], v[136:139], v[166:169], v[2:17]
	global_load_dwordx4 v[166:169], v[212:213], off offset:1024
	s_waitcnt vmcnt(15)
	v_mfma_f32_32x32x16_bf16 v[50:65], v[120:123], v[170:173], v[50:65]
	v_mfma_f32_32x32x16_bf16 v[34:49], v[124:127], v[170:173], v[34:49]
	v_mfma_f32_32x32x16_bf16 v[18:33], v[128:131], v[170:173], v[18:33]
	v_mfma_f32_32x32x16_bf16 v[2:17], v[132:135], v[170:173], v[2:17]
	global_load_dwordx4 v[170:173], v[88:89], off offset:1024
	ds_read_b128 v[120:123], v68 offset:3072
	ds_read_b128 v[124:127], v68 offset:15360
	ds_read_b128 v[128:131], v68 offset:27648
	ds_read_b128 v[132:135], v91 offset:3072
	ds_read_b128 v[136:139], v91 offset:15360
	ds_read_b128 v[218:221], v91 offset:27648
	ds_read_b128 v[222:225], v91 offset:39936
	s_waitcnt vmcnt(15) lgkmcnt(7)
	v_mfma_f32_32x32x16_bf16 v[50:65], v[104:107], v[174:177], v[50:65]
	v_mfma_f32_32x32x16_bf16 v[34:49], v[108:111], v[174:177], v[34:49]
	v_mfma_f32_32x32x16_bf16 v[18:33], v[112:115], v[174:177], v[18:33]
	v_mfma_f32_32x32x16_bf16 v[2:17], v[116:119], v[174:177], v[2:17]
	global_load_dwordx4 v[174:177], v[140:141], off offset:2048
	s_waitcnt vmcnt(15)
	v_mfma_f32_32x32x16_bf16 v[50:65], v[100:103], v[178:181], v[50:65]
	v_mfma_f32_32x32x16_bf16 v[34:49], v[104:107], v[178:181], v[34:49]
	v_mfma_f32_32x32x16_bf16 v[18:33], v[108:111], v[178:181], v[18:33]
	v_mfma_f32_32x32x16_bf16 v[2:17], v[112:115], v[178:181], v[2:17]
	global_load_dwordx4 v[178:181], v[210:211], off offset:2048
	s_waitcnt vmcnt(15)
	v_mfma_f32_32x32x16_bf16 v[50:65], v[96:99], v[182:185], v[50:65]
	v_mfma_f32_32x32x16_bf16 v[34:49], v[100:103], v[182:185], v[34:49]
	v_mfma_f32_32x32x16_bf16 v[18:33], v[104:107], v[182:185], v[18:33]
	v_mfma_f32_32x32x16_bf16 v[2:17], v[108:111], v[182:185], v[2:17]
	global_load_dwordx4 v[182:185], v[212:213], off offset:2048
	s_waitcnt vmcnt(15)
	v_mfma_f32_32x32x16_bf16 v[50:65], v[84:87], v[190:193], v[50:65]
	v_mfma_f32_32x32x16_bf16 v[34:49], v[96:99], v[190:193], v[34:49]
	v_mfma_f32_32x32x16_bf16 v[18:33], v[100:103], v[190:193], v[18:33]
	v_mfma_f32_32x32x16_bf16 v[2:17], v[104:107], v[190:193], v[2:17]
	global_load_dwordx4 v[190:193], v[88:89], off offset:2048
	ds_read_b128 v[84:87], v68 offset:2304
	ds_read_b128 v[96:99], v68 offset:14592
	ds_read_b128 v[100:103], v68 offset:26880
	ds_read_b128 v[104:107], v91 offset:2304
	ds_read_b128 v[108:111], v91 offset:14592
	ds_read_b128 v[112:115], v91 offset:26880
	ds_read_b128 v[116:119], v91 offset:39168
	s_waitcnt vmcnt(15) lgkmcnt(7)
	v_mfma_f32_32x32x16_bf16 v[50:65], v[132:135], v[194:197], v[50:65]
	v_mfma_f32_32x32x16_bf16 v[34:49], v[136:139], v[194:197], v[34:49]
	v_mfma_f32_32x32x16_bf16 v[18:33], v[218:221], v[194:197], v[18:33]
	v_mfma_f32_32x32x16_bf16 v[2:17], v[222:225], v[194:197], v[2:17]
	global_load_dwordx4 v[194:197], v[140:141], off offset:3072
	s_waitcnt vmcnt(15)
	v_mfma_f32_32x32x16_bf16 v[50:65], v[128:131], v[198:201], v[50:65]
	v_mfma_f32_32x32x16_bf16 v[34:49], v[132:135], v[198:201], v[34:49]
	v_mfma_f32_32x32x16_bf16 v[18:33], v[136:139], v[198:201], v[18:33]
	v_mfma_f32_32x32x16_bf16 v[2:17], v[218:221], v[198:201], v[2:17]
	global_load_dwordx4 v[198:201], v[210:211], off offset:3072
	s_waitcnt vmcnt(15)
	v_mfma_f32_32x32x16_bf16 v[50:65], v[124:127], v[202:205], v[50:65]
	v_mfma_f32_32x32x16_bf16 v[34:49], v[128:131], v[202:205], v[34:49]
	v_mfma_f32_32x32x16_bf16 v[18:33], v[132:135], v[202:205], v[18:33]
	v_mfma_f32_32x32x16_bf16 v[2:17], v[136:139], v[202:205], v[2:17]
	global_load_dwordx4 v[202:205], v[212:213], off offset:3072
	s_waitcnt vmcnt(15)
	v_mfma_f32_32x32x16_bf16 v[50:65], v[120:123], v[206:209], v[50:65]
	v_mfma_f32_32x32x16_bf16 v[34:49], v[124:127], v[206:209], v[34:49]
	v_mfma_f32_32x32x16_bf16 v[18:33], v[128:131], v[206:209], v[18:33]
	v_mfma_f32_32x32x16_bf16 v[2:17], v[132:135], v[206:209], v[2:17]
	global_load_dwordx4 v[206:209], v[88:89], off offset:3072
	s_ashr_i32 s25, s24, 31
	s_mul_i32 s49, s26, 0x24000
	s_lshl_b64 s[28:29], s[24:25], 14
	s_lshl_b64 s[34:35], s[26:27], 19
	s_mul_hi_i32 s31, s26, 0x24000
	s_add_u32 s28, s49, s28
	s_addc_u32 s29, s31, s29
	s_add_u32 s28, s28, 0x800
	s_addc_u32 s29, s29, 0
	s_add_u32 s34, s34, 0x9901000
	s_addc_u32 s35, s35, 0
	v_lshl_add_u64 v[88:89], v[80:81], 0, s[28:29]
	v_lshl_add_u64 v[214:215], v[78:79], 0, s[34:35]
	s_mov_b64 s[28:29], 0x20000
	v_lshl_add_u64 v[216:217], v[214:215], 0, s[28:29]
	v_lshl_add_u64 v[140:141], v[216:217], 0, s[28:29]
	v_lshl_add_u64 v[186:187], v[140:141], 0, s[28:29]
	ds_read_b128 v[120:123], v68 offset:1536
	ds_read_b128 v[124:127], v68 offset:13824
	ds_read_b128 v[128:131], v68 offset:26112
	ds_read_b128 v[132:135], v91 offset:1536
	ds_read_b128 v[136:139], v91 offset:13824
	ds_read_b128 v[218:221], v91 offset:26112
	ds_read_b128 v[222:225], v91 offset:38400
	s_waitcnt vmcnt(15) lgkmcnt(7)
	v_mfma_f32_32x32x16_bf16 v[50:65], v[104:107], v[142:145], v[50:65]
	v_mfma_f32_32x32x16_bf16 v[34:49], v[108:111], v[142:145], v[34:49]
	v_mfma_f32_32x32x16_bf16 v[18:33], v[112:115], v[142:145], v[18:33]
	v_mfma_f32_32x32x16_bf16 v[2:17], v[116:119], v[142:145], v[2:17]
	global_load_dwordx4 v[142:145], v[88:89], off offset:-4096
	s_waitcnt vmcnt(15)
	v_mfma_f32_32x32x16_bf16 v[50:65], v[100:103], v[146:149], v[50:65]
	v_mfma_f32_32x32x16_bf16 v[34:49], v[104:107], v[146:149], v[34:49]
	v_mfma_f32_32x32x16_bf16 v[18:33], v[108:111], v[146:149], v[18:33]
	v_mfma_f32_32x32x16_bf16 v[2:17], v[112:115], v[146:149], v[2:17]
	global_load_dwordx4 v[146:149], v[214:215], off offset:-4096
	s_waitcnt vmcnt(15)
; #define GAS __attribute__((address_space(1)))
; #define LAS __attribute__((address_space(3)))
; __device__ __forceinline__ void ph_s5_out(Frame& F) {
;     ...
;         for (int s0 = 0; s0 < 64; s0 += 16) {
;             bf16x8_t bq[16];
; #pragma unroll
;             for (int e = 0; e < 16; ++e) bq[e] = *(const GAS bf16x8_t*)(ub + 512 * (s0 + e));
; #pragma unroll
;             for (int e = 0; e < 16; ++e) { const int sI = s0 + e; const bf16x8_t b = bq[e];
; #pragma unroll
;             for (int i = 0; i < 4; ++i) { const bf16x8_t a = *(const LAS bf16x8_t*)(tl + (16 * i - sI) * 16 * TP_PITCH); acc[i] = __builtin_amdgcn_mfma_f32_32x32x16_bf16(a, b, acc[i], 0, 0, 0); }
;             }
	v_mfma_f32_32x32x16_bf16 v[50:65], v[96:99], v[150:153], v[50:65]
	v_mfma_f32_32x32x16_bf16 v[34:49], v[100:103], v[150:153], v[34:49]
	v_mfma_f32_32x32x16_bf16 v[18:33], v[104:107], v[150:153], v[18:33]
	v_mfma_f32_32x32x16_bf16 v[2:17], v[108:111], v[150:153], v[2:17]
	global_load_dwordx4 v[150:153], v[216:217], off offset:-4096
	s_waitcnt vmcnt(15)
	v_mfma_f32_32x32x16_bf16 v[50:65], v[84:87], v[154:157], v[50:65]
	v_mfma_f32_32x32x16_bf16 v[34:49], v[96:99], v[154:157], v[34:49]
	v_mfma_f32_32x32x16_bf16 v[18:33], v[100:103], v[154:157], v[18:33]
	v_mfma_f32_32x32x16_bf16 v[2:17], v[104:107], v[154:157], v[2:17]
	global_load_dwordx4 v[154:157], v[140:141], off offset:-4096
	ds_read_b128 v[84:87], v68 offset:768
	ds_read_b128 v[96:99], v68 offset:13056
	ds_read_b128 v[100:103], v68 offset:25344
	ds_read_b128 v[104:107], v91 offset:768
	ds_read_b128 v[108:111], v91 offset:13056
	ds_read_b128 v[112:115], v91 offset:25344
	ds_read_b128 v[116:119], v91 offset:37632
	s_waitcnt vmcnt(15) lgkmcnt(7)
	v_mfma_f32_32x32x16_bf16 v[50:65], v[132:135], v[158:161], v[50:65]
	v_mfma_f32_32x32x16_bf16 v[34:49], v[136:139], v[158:161], v[34:49]
	v_mfma_f32_32x32x16_bf16 v[18:33], v[218:221], v[158:161], v[18:33]
	v_mfma_f32_32x32x16_bf16 v[2:17], v[222:225], v[158:161], v[2:17]
	global_load_dwordx4 v[158:161], v[186:187], off offset:-4096
	s_waitcnt vmcnt(15)
	v_mfma_f32_32x32x16_bf16 v[50:65], v[128:131], v[162:165], v[50:65]
	v_mfma_f32_32x32x16_bf16 v[34:49], v[132:135], v[162:165], v[34:49]
	v_mfma_f32_32x32x16_bf16 v[18:33], v[136:139], v[162:165], v[18:33]
	v_mfma_f32_32x32x16_bf16 v[2:17], v[218:221], v[162:165], v[2:17]
	global_load_dwordx4 v[162:165], v[88:89], off offset:-3072
	s_waitcnt vmcnt(15)
	v_mfma_f32_32x32x16_bf16 v[50:65], v[124:127], v[166:169], v[50:65]
	v_mfma_f32_32x32x16_bf16 v[34:49], v[128:131], v[166:169], v[34:49]
	v_mfma_f32_32x32x16_bf16 v[18:33], v[132:135], v[166:169], v[18:33]
	v_mfma_f32_32x32x16_bf16 v[2:17], v[136:139], v[166:169], v[2:17]
	global_load_dwordx4 v[166:169], v[214:215], off offset:-3072
	s_waitcnt vmcnt(15)
	v_mfma_f32_32x32x16_bf16 v[50:65], v[120:123], v[170:173], v[50:65]
	v_mfma_f32_32x32x16_bf16 v[34:49], v[124:127], v[170:173], v[34:49]
	v_mfma_f32_32x32x16_bf16 v[18:33], v[128:131], v[170:173], v[18:33]
	v_mfma_f32_32x32x16_bf16 v[2:17], v[132:135], v[170:173], v[2:17]
	global_load_dwordx4 v[170:173], v[216:217], off offset:-3072
	ds_read_b128 v[120:123], v68 offset:0
	ds_read_b128 v[124:127], v68 offset:12288
	ds_read_b128 v[128:131], v68 offset:24576
	ds_read_b128 v[132:135], v91 offset:0
	ds_read_b128 v[136:139], v91 offset:12288
	ds_read_b128 v[218:221], v91 offset:24576
	ds_read_b128 v[222:225], v91 offset:36864
	s_waitcnt vmcnt(15) lgkmcnt(7)
	v_mfma_f32_32x32x16_bf16 v[50:65], v[104:107], v[174:177], v[50:65]
	v_mfma_f32_32x32x16_bf16 v[34:49], v[108:111], v[174:177], v[34:49]
	v_mfma_f32_32x32x16_bf16 v[18:33], v[112:115], v[174:177], v[18:33]
	v_mfma_f32_32x32x16_bf16 v[2:17], v[116:119], v[174:177], v[2:17]
	global_load_dwordx4 v[174:177], v[140:141], off offset:-3072
	s_waitcnt vmcnt(15)
	v_mfma_f32_32x32x16_bf16 v[50:65], v[100:103], v[178:181], v[50:65]
	v_mfma_f32_32x32x16_bf16 v[34:49], v[104:107], v[178:181], v[34:49]
	v_mfma_f32_32x32x16_bf16 v[18:33], v[108:111], v[178:181], v[18:33]
	v_mfma_f32_32x32x16_bf16 v[2:17], v[112:115], v[178:181], v[2:17]
	global_load_dwordx4 v[178:181], v[186:187], off offset:-3072
	s_waitcnt vmcnt(15)
	v_mfma_f32_32x32x16_bf16 v[50:65], v[96:99], v[182:185], v[50:65]
	v_mfma_f32_32x32x16_bf16 v[34:49], v[100:103], v[182:185], v[34:49]
	v_mfma_f32_32x32x16_bf16 v[18:33], v[104:107], v[182:185], v[18:33]
	v_mfma_f32_32x32x16_bf16 v[2:17], v[108:111], v[182:185], v[2:17]
	global_load_dwordx4 v[182:185], v[88:89], off offset:-2048
	s_waitcnt vmcnt(15)
	v_mfma_f32_32x32x16_bf16 v[50:65], v[84:87], v[190:193], v[50:65]
	v_mfma_f32_32x32x16_bf16 v[34:49], v[96:99], v[190:193], v[34:49]
	v_mfma_f32_32x32x16_bf16 v[18:33], v[100:103], v[190:193], v[18:33]
	v_mfma_f32_32x32x16_bf16 v[2:17], v[104:107], v[190:193], v[2:17]
	global_load_dwordx4 v[190:193], v[214:215], off offset:-2048
	s_waitcnt vmcnt(15) lgkmcnt(0)
	v_mfma_f32_32x32x16_bf16 v[50:65], v[132:135], v[194:197], v[50:65]
	v_mfma_f32_32x32x16_bf16 v[34:49], v[136:139], v[194:197], v[34:49]
	v_mfma_f32_32x32x16_bf16 v[18:33], v[218:221], v[194:197], v[18:33]
	v_mfma_f32_32x32x16_bf16 v[2:17], v[222:225], v[194:197], v[2:17]
	global_load_dwordx4 v[194:197], v[216:217], off offset:-2048
	s_waitcnt vmcnt(15)
	v_mfma_f32_32x32x16_bf16 v[50:65], v[128:131], v[198:201], v[50:65]
	v_mfma_f32_32x32x16_bf16 v[34:49], v[132:135], v[198:201], v[34:49]
	v_mfma_f32_32x32x16_bf16 v[18:33], v[136:139], v[198:201], v[18:33]
	v_mfma_f32_32x32x16_bf16 v[2:17], v[218:221], v[198:201], v[2:17]
	global_load_dwordx4 v[198:201], v[140:141], off offset:-2048
	s_waitcnt vmcnt(15)
	v_mfma_f32_32x32x16_bf16 v[50:65], v[124:127], v[202:205], v[50:65]
	v_mfma_f32_32x32x16_bf16 v[34:49], v[128:131], v[202:205], v[34:49]
	v_mfma_f32_32x32x16_bf16 v[18:33], v[132:135], v[202:205], v[18:33]
	v_mfma_f32_32x32x16_bf16 v[2:17], v[136:139], v[202:205], v[2:17]
	global_load_dwordx4 v[202:205], v[186:187], off offset:-2048
	s_waitcnt vmcnt(15)
; #define GAS __attribute__((address_space(1)))
; #define LAS __attribute__((address_space(3)))
; __device__ __forceinline__ void ph_s5_out(Frame& F) {
;     ...
;             for (int i = 0; i < 4; ++i) { const bf16x8_t a = *(const LAS bf16x8_t*)(tl + (16 * i - sI) * 16 * TP_PITCH); acc[i] = __builtin_amdgcn_mfma_f32_32x32x16_bf16(a, b, acc[i], 0, 0, 0); }
;             }
;         }
;         { const bf16* sb = (const bf16*)(ws + WS_SIN) + (size_t)g * 9 * 16 * 512 + ((size_t)nb * 16 * 64 + lane) * 8;
;           const bf16* wc = (const bf16*)(ws + WS_WC) + (size_t)g * 1024 * 256 + (((size_t)wave * 16) * 64 + lane) * 8;
; #pragma unroll 4
;           for (int kk = 0; kk < 16; ++kk) {
;               const bf16x8_t b = *(const GAS bf16x8_t*)(sb + 512 * kk);
; #pragma unroll
;               for (int i = 0; i < 4; ++i) { const bf16x8_t a = *(const GAS bf16x8_t*)(wc + (size_t)(8 * i) * 16 * 512 + 512 * kk); acc[i] = __builtin_amdgcn_mfma_f32_32x32x16_bf16(a, b, acc[i], 0, 0, 0); }
;           } }
	v_mfma_f32_32x32x16_bf16 v[50:65], v[120:123], v[206:209], v[50:65]
	v_mfma_f32_32x32x16_bf16 v[34:49], v[124:127], v[206:209], v[34:49]
	v_mfma_f32_32x32x16_bf16 v[18:33], v[128:131], v[206:209], v[18:33]
	v_mfma_f32_32x32x16_bf16 v[2:17], v[132:135], v[206:209], v[2:17]
	global_load_dwordx4 v[206:209], v[88:89], off offset:-1024
	global_load_dwordx4 v[96:99], v[214:215], off offset:-1024
	global_load_dwordx4 v[100:103], v[216:217], off offset:-1024
	global_load_dwordx4 v[104:107], v[140:141], off offset:-1024
	global_load_dwordx4 v[108:111], v[186:187], off offset:-1024
	global_load_dwordx4 v[112:115], v[88:89], off
	global_load_dwordx4 v[116:119], v[214:215], off
	global_load_dwordx4 v[120:123], v[216:217], off
	global_load_dwordx4 v[124:127], v[140:141], off
	global_load_dwordx4 v[128:131], v[186:187], off
	global_load_dwordx4 v[132:135], v[88:89], off offset:1024
	global_load_dwordx4 v[136:139], v[214:215], off offset:1024
	s_waitcnt vmcnt(25)
	v_mfma_f32_32x32x16_bf16 v[50:65], v[146:149], v[142:145], v[50:65]
	global_load_dwordx4 v[146:149], v[216:217], off offset:1024
	s_waitcnt vmcnt(25)
	v_mfma_f32_32x32x16_bf16 v[34:49], v[150:153], v[142:145], v[34:49]
	global_load_dwordx4 v[150:153], v[140:141], off offset:1024
	s_waitcnt vmcnt(25)
	v_mfma_f32_32x32x16_bf16 v[18:33], v[154:157], v[142:145], v[18:33]
	global_load_dwordx4 v[154:157], v[186:187], off offset:1024
	s_waitcnt vmcnt(25)
	v_mfma_f32_32x32x16_bf16 v[2:17], v[158:161], v[142:145], v[2:17]
	global_load_dwordx4 v[158:161], v[88:89], off offset:2048
	global_load_dwordx4 v[142:145], v[214:215], off offset:2048
	s_waitcnt vmcnt(25)
	v_mfma_f32_32x32x16_bf16 v[50:65], v[166:169], v[162:165], v[50:65]
	global_load_dwordx4 v[166:169], v[216:217], off offset:2048
	s_waitcnt vmcnt(25)
	v_mfma_f32_32x32x16_bf16 v[34:49], v[170:173], v[162:165], v[34:49]
	global_load_dwordx4 v[170:173], v[140:141], off offset:2048
	s_waitcnt vmcnt(25)
	v_mfma_f32_32x32x16_bf16 v[18:33], v[174:177], v[162:165], v[18:33]
	global_load_dwordx4 v[174:177], v[186:187], off offset:2048
	s_waitcnt vmcnt(25)
	v_mfma_f32_32x32x16_bf16 v[2:17], v[178:181], v[162:165], v[2:17]
	global_load_dwordx4 v[178:181], v[88:89], off offset:3072
	global_load_dwordx4 v[162:165], v[214:215], off offset:3072
	s_waitcnt vmcnt(25)
	v_mfma_f32_32x32x16_bf16 v[50:65], v[190:193], v[182:185], v[50:65]
	global_load_dwordx4 v[190:193], v[216:217], off offset:3072
	s_waitcnt vmcnt(25)
	v_mfma_f32_32x32x16_bf16 v[34:49], v[194:197], v[182:185], v[34:49]
	global_load_dwordx4 v[194:197], v[140:141], off offset:3072
	s_waitcnt vmcnt(25)
	v_mfma_f32_32x32x16_bf16 v[18:33], v[198:201], v[182:185], v[18:33]
	global_load_dwordx4 v[198:201], v[186:187], off offset:3072
	s_waitcnt vmcnt(25)
	v_mfma_f32_32x32x16_bf16 v[2:17], v[202:205], v[182:185], v[2:17]
	v_lshl_add_u64 v[88:89], v[88:89], 0, s[20:21]
	v_lshl_add_u64 v[214:215], v[214:215], 0, s[20:21]
	v_lshl_add_u64 v[216:217], v[216:217], 0, s[20:21]
	v_lshl_add_u64 v[140:141], v[140:141], 0, s[20:21]
	v_lshl_add_u64 v[186:187], v[186:187], 0, s[20:21]
	global_load_dwordx4 v[202:205], v[88:89], off offset:-4096
	global_load_dwordx4 v[182:185], v[214:215], off offset:-4096
	s_waitcnt vmcnt(25)
	v_mfma_f32_32x32x16_bf16 v[50:65], v[96:99], v[206:209], v[50:65]
	global_load_dwordx4 v[96:99], v[216:217], off offset:-4096
	s_waitcnt vmcnt(25)
	v_mfma_f32_32x32x16_bf16 v[34:49], v[100:103], v[206:209], v[34:49]
	global_load_dwordx4 v[100:103], v[140:141], off offset:-4096
	s_waitcnt vmcnt(25)
	v_mfma_f32_32x32x16_bf16 v[18:33], v[104:107], v[206:209], v[18:33]
	global_load_dwordx4 v[104:107], v[186:187], off offset:-4096
	s_waitcnt vmcnt(25)
	v_mfma_f32_32x32x16_bf16 v[2:17], v[108:111], v[206:209], v[2:17]
	global_load_dwordx4 v[108:111], v[88:89], off offset:-3072
	global_load_dwordx4 v[206:209], v[214:215], off offset:-3072
	s_waitcnt vmcnt(25)
	v_mfma_f32_32x32x16_bf16 v[50:65], v[116:119], v[112:115], v[50:65]
	global_load_dwordx4 v[116:119], v[216:217], off offset:-3072
	s_waitcnt vmcnt(25)
	v_mfma_f32_32x32x16_bf16 v[34:49], v[120:123], v[112:115], v[34:49]
	global_load_dwordx4 v[120:123], v[140:141], off offset:-3072
	s_waitcnt vmcnt(25)
	v_mfma_f32_32x32x16_bf16 v[18:33], v[124:127], v[112:115], v[18:33]
	global_load_dwordx4 v[124:127], v[186:187], off offset:-3072
	s_waitcnt vmcnt(25)
	v_mfma_f32_32x32x16_bf16 v[2:17], v[128:131], v[112:115], v[2:17]
	global_load_dwordx4 v[128:131], v[88:89], off offset:-2048
	global_load_dwordx4 v[112:115], v[214:215], off offset:-2048
	s_waitcnt vmcnt(25)
	v_mfma_f32_32x32x16_bf16 v[50:65], v[136:139], v[132:135], v[50:65]
	global_load_dwordx4 v[136:139], v[216:217], off offset:-2048
	s_waitcnt vmcnt(25)
	v_mfma_f32_32x32x16_bf16 v[34:49], v[146:149], v[132:135], v[34:49]
	global_load_dwordx4 v[146:149], v[140:141], off offset:-2048
	s_waitcnt vmcnt(25)
	v_mfma_f32_32x32x16_bf16 v[18:33], v[150:153], v[132:135], v[18:33]
	global_load_dwordx4 v[150:153], v[186:187], off offset:-2048
	s_waitcnt vmcnt(25)
	v_mfma_f32_32x32x16_bf16 v[2:17], v[154:157], v[132:135], v[2:17]
	global_load_dwordx4 v[154:157], v[88:89], off offset:-1024
	global_load_dwordx4 v[132:135], v[214:215], off offset:-1024
	s_waitcnt vmcnt(25)
	v_mfma_f32_32x32x16_bf16 v[50:65], v[142:145], v[158:161], v[50:65]
	global_load_dwordx4 v[142:145], v[216:217], off offset:-1024
	s_waitcnt vmcnt(25)
	v_mfma_f32_32x32x16_bf16 v[34:49], v[166:169], v[158:161], v[34:49]
	global_load_dwordx4 v[166:169], v[140:141], off offset:-1024
	s_waitcnt vmcnt(25)
	v_mfma_f32_32x32x16_bf16 v[18:33], v[170:173], v[158:161], v[18:33]
	global_load_dwordx4 v[170:173], v[186:187], off offset:-1024
	s_waitcnt vmcnt(25)
; #define GAS __attribute__((address_space(1)))
; __device__ __forceinline__ void ph_s5_out(Frame& F) {
;     ...
;           for (int kk = 0; kk < 16; ++kk) {
;               const bf16x8_t b = *(const GAS bf16x8_t*)(sb + 512 * kk);
; #pragma unroll
;               for (int i = 0; i < 4; ++i) { const bf16x8_t a = *(const GAS bf16x8_t*)(wc + (size_t)(8 * i) * 16 * 512 + 512 * kk); acc[i] = __builtin_amdgcn_mfma_f32_32x32x16_bf16(a, b, acc[i], 0, 0, 0); }
;           } }
;         if (valid) {
	v_mfma_f32_32x32x16_bf16 v[2:17], v[174:177], v[158:161], v[2:17]
	global_load_dwordx4 v[174:177], v[88:89], off
	global_load_dwordx4 v[158:161], v[214:215], off
	s_waitcnt vmcnt(25)
	v_mfma_f32_32x32x16_bf16 v[50:65], v[162:165], v[178:181], v[50:65]
	global_load_dwordx4 v[162:165], v[216:217], off
	s_waitcnt vmcnt(25)
	v_mfma_f32_32x32x16_bf16 v[34:49], v[190:193], v[178:181], v[34:49]
	global_load_dwordx4 v[190:193], v[140:141], off
	s_waitcnt vmcnt(25)
	v_mfma_f32_32x32x16_bf16 v[18:33], v[194:197], v[178:181], v[18:33]
	global_load_dwordx4 v[194:197], v[186:187], off
	s_waitcnt vmcnt(25)
	v_mfma_f32_32x32x16_bf16 v[2:17], v[198:201], v[178:181], v[2:17]
	global_load_dwordx4 v[198:201], v[88:89], off offset:1024
	global_load_dwordx4 v[178:181], v[214:215], off offset:1024
	s_waitcnt vmcnt(25)
	v_mfma_f32_32x32x16_bf16 v[50:65], v[182:185], v[202:205], v[50:65]
	global_load_dwordx4 v[182:185], v[216:217], off offset:1024
	s_waitcnt vmcnt(25)
	v_mfma_f32_32x32x16_bf16 v[34:49], v[96:99], v[202:205], v[34:49]
	global_load_dwordx4 v[96:99], v[140:141], off offset:1024
	s_waitcnt vmcnt(25)
	v_mfma_f32_32x32x16_bf16 v[18:33], v[100:103], v[202:205], v[18:33]
	global_load_dwordx4 v[100:103], v[186:187], off offset:1024
	s_waitcnt vmcnt(25)
	v_mfma_f32_32x32x16_bf16 v[2:17], v[104:107], v[202:205], v[2:17]
	global_load_dwordx4 v[104:107], v[88:89], off offset:2048
	global_load_dwordx4 v[202:205], v[214:215], off offset:2048
	s_waitcnt vmcnt(25)
	v_mfma_f32_32x32x16_bf16 v[50:65], v[206:209], v[108:111], v[50:65]
	global_load_dwordx4 v[206:209], v[216:217], off offset:2048
	s_waitcnt vmcnt(25)
	v_mfma_f32_32x32x16_bf16 v[34:49], v[116:119], v[108:111], v[34:49]
	global_load_dwordx4 v[116:119], v[140:141], off offset:2048
	s_waitcnt vmcnt(25)
	v_mfma_f32_32x32x16_bf16 v[18:33], v[120:123], v[108:111], v[18:33]
	global_load_dwordx4 v[120:123], v[186:187], off offset:2048
	s_waitcnt vmcnt(25)
	v_mfma_f32_32x32x16_bf16 v[2:17], v[124:127], v[108:111], v[2:17]
	global_load_dwordx4 v[124:127], v[88:89], off offset:3072
	global_load_dwordx4 v[108:111], v[214:215], off offset:3072
	s_waitcnt vmcnt(25)
	v_mfma_f32_32x32x16_bf16 v[50:65], v[112:115], v[128:131], v[50:65]
	global_load_dwordx4 v[112:115], v[216:217], off offset:3072
	s_waitcnt vmcnt(25)
	v_mfma_f32_32x32x16_bf16 v[34:49], v[136:139], v[128:131], v[34:49]
	global_load_dwordx4 v[136:139], v[140:141], off offset:3072
	s_waitcnt vmcnt(25)
	v_mfma_f32_32x32x16_bf16 v[18:33], v[146:149], v[128:131], v[18:33]
	global_load_dwordx4 v[146:149], v[186:187], off offset:3072
	s_waitcnt vmcnt(25)
	v_mfma_f32_32x32x16_bf16 v[2:17], v[150:153], v[128:131], v[2:17]
	s_waitcnt vmcnt(23)
	v_mfma_f32_32x32x16_bf16 v[50:65], v[132:135], v[154:157], v[50:65]
	s_waitcnt vmcnt(22)
	v_mfma_f32_32x32x16_bf16 v[34:49], v[142:145], v[154:157], v[34:49]
	s_waitcnt vmcnt(21)
	v_mfma_f32_32x32x16_bf16 v[18:33], v[166:169], v[154:157], v[18:33]
	s_waitcnt vmcnt(20)
	v_mfma_f32_32x32x16_bf16 v[2:17], v[170:173], v[154:157], v[2:17]
	s_waitcnt vmcnt(18)
	v_mfma_f32_32x32x16_bf16 v[50:65], v[158:161], v[174:177], v[50:65]
	s_waitcnt vmcnt(17)
	v_mfma_f32_32x32x16_bf16 v[34:49], v[162:165], v[174:177], v[34:49]
	s_waitcnt vmcnt(16)
	v_mfma_f32_32x32x16_bf16 v[18:33], v[190:193], v[174:177], v[18:33]
	s_waitcnt vmcnt(15)
	v_mfma_f32_32x32x16_bf16 v[2:17], v[194:197], v[174:177], v[2:17]
	s_waitcnt vmcnt(13)
	v_mfma_f32_32x32x16_bf16 v[50:65], v[178:181], v[198:201], v[50:65]
	s_waitcnt vmcnt(12)
	v_mfma_f32_32x32x16_bf16 v[34:49], v[182:185], v[198:201], v[34:49]
	s_waitcnt vmcnt(11)
	v_mfma_f32_32x32x16_bf16 v[18:33], v[96:99], v[198:201], v[18:33]
	s_waitcnt vmcnt(10)
	v_mfma_f32_32x32x16_bf16 v[2:17], v[100:103], v[198:201], v[2:17]
	s_waitcnt vmcnt(8)
	v_mfma_f32_32x32x16_bf16 v[50:65], v[202:205], v[104:107], v[50:65]
	s_waitcnt vmcnt(7)
	v_mfma_f32_32x32x16_bf16 v[34:49], v[206:209], v[104:107], v[34:49]
	s_waitcnt vmcnt(6)
	v_mfma_f32_32x32x16_bf16 v[18:33], v[116:119], v[104:107], v[18:33]
	s_waitcnt vmcnt(5)
	v_mfma_f32_32x32x16_bf16 v[2:17], v[120:123], v[104:107], v[2:17]
	s_waitcnt vmcnt(3)
	v_mfma_f32_32x32x16_bf16 v[50:65], v[108:111], v[124:127], v[50:65]
	s_waitcnt vmcnt(2)
	v_mfma_f32_32x32x16_bf16 v[34:49], v[112:115], v[124:127], v[34:49]
	s_waitcnt vmcnt(1)
	v_mfma_f32_32x32x16_bf16 v[18:33], v[136:139], v[124:127], v[18:33]
	s_waitcnt vmcnt(0)
	v_mfma_f32_32x32x16_bf16 v[2:17], v[146:149], v[124:127], v[2:17]
	v_lshl_or_b32 v82, s24, 5, v1
	v_cmp_gt_i32_e32 vcc, s45, v82
	s_and_saveexec_b64 s[24:25], vcc
	s_cbranch_execz .LBB0_963
; #define GAS __attribute__((address_space(1)))
; __device__ __forceinline__ unsigned pk2(float lo, float hi) { const f32x2cv v = {lo, hi}; return __builtin_bit_cast(unsigned, __builtin_convertvector(v, bf16x2cv)); }
; __device__ __forceinline__ float gelu_tanh(float x) { const float u = 0.7978845608028654f * (x + 0.044715f * x * x * x); return x * __builtin_amdgcn_rcpf(1.0f + __builtin_amdgcn_exp2f(-2.8853900817779268f * u)); }
; __device__ __forceinline__ void ph_s5_out(Frame& F) {
;     ...
;         if (valid) {
;             const float* dsk = inp(F, 24) + 16 * g;
; #pragma unroll
;             for (int i = 0; i < 4; ++i)
; #pragma unroll
;                 for (int k = 0; k < 4; ++k) { const int tloc = 2 * (wave + 8 * i) + (k >> 1), p0 = 8 * (k & 1) + 4 * hh; const size_t m = (size_t)chunk * 64 + tloc;
;                     const v2u uw = *(const GAS v2u*)((chunk < 256 ? (const bf16*)(ws + WS_UG) : (const bf16*)(ws + WS_UGC)) + ug_index(g, (int)m, p0));
;                     const float y0 = gelu_tanh(acc[i][4 * k] + dsk[p0] * bflo(uw.x)), y1 = gelu_tanh(acc[i][4 * k + 1] + dsk[p0 + 1] * bfhi(uw.x));
;                     const float y2 = gelu_tanh(acc[i][4 * k + 2] + dsk[p0 + 2] * bflo(uw.y)), y3 = gelu_tanh(acc[i][4 * k + 3] + dsk[p0 + 3] * bfhi(uw.y));
;                     v2u zw; zw.x = pk2(y0, y1); zw.y = pk2(y2, y3);
;                     *(GAS v2u*)((bf16*)(ws + WS_Z) + m * 512 + 16 * g + p0) = zw; }
	v_mov_b32_e32 v68, s46
	ds_read_b64 v[84:85], v68
	v_ashrrev_i32_e32 v83, 31, v82
	v_lshlrev_b64 v[88:89], 6, v[82:83]
	v_cmp_gt_i32_e32 vcc, s47, v82
	v_lshl_add_u64 v[102:103], v[88:89], 0, s[4:5]
	v_ashrrev_i32_e32 v83, 11, v102
	v_cndmask_b32_e32 v68, v94, v95, vcc
	v_lshl_add_u64 v[86:87], v[70:71], 0, v[68:69]
	v_ashrrev_i32_e32 v68, 6, v102
	v_add_u32_e32 v83, s30, v83
	v_mov_b32_e32 v96, s26
	v_cmp_gt_i32_e32 vcc, s47, v68
	s_lshl_b32 s28, s26, 4
	s_waitcnt lgkmcnt(0)
	v_readfirstlane_b32 s27, v84
	v_and_b32_e32 v97, 31, v68
	v_cndmask_b32_e32 v84, v96, v83, vcc
	s_ashr_i32 s29, s28, 31
	v_readfirstlane_b32 s31, v85
	v_or_b32_e32 v82, v97, v67
	v_ashrrev_i32_e32 v85, 31, v84
	v_lshlrev_b32_e32 v68, 6, v102
	s_lshl_b64 s[34:35], s[28:29], 2
	v_and_b32_e32 v68, 0xf80, v68
	v_ashrrev_i32_e32 v83, 31, v82
	v_lshlrev_b64 v[84:85], 16, v[84:85]
	v_lshl_add_u64 v[82:83], v[68:69], 0, v[82:83]
	v_lshl_add_u64 v[104:105], v[86:87], 0, v[84:85]
	s_add_u32 s26, s27, s34
	v_lshl_add_u64 v[82:83], v[82:83], 4, v[104:105]
	s_addc_u32 s27, s31, s35
	v_lshl_add_u64 v[98:99], v[188:189], 2, s[26:27]
	global_load_dwordx4 v[174:177], v[98:99], off
	global_load_dwordx4 v[178:181], v[98:99], off offset:32
	global_load_dwordx2 v[142:143], v[82:83], off
	global_load_dwordx2 v[144:145], v[82:83], off offset:512
	global_load_dwordx2 v[146:147], v[82:83], off offset:1024
	global_load_dwordx2 v[148:149], v[82:83], off offset:1536
	v_lshl_add_u64 v[82:83], v[82:83], 0, s[22:23]
	global_load_dwordx2 v[150:151], v[82:83], off
	global_load_dwordx2 v[152:153], v[82:83], off offset:512
	global_load_dwordx2 v[154:155], v[82:83], off offset:1024
	global_load_dwordx2 v[156:157], v[82:83], off offset:1536
	v_lshl_add_u64 v[82:83], v[82:83], 0, s[22:23]
	global_load_dwordx2 v[158:159], v[82:83], off
	global_load_dwordx2 v[160:161], v[82:83], off offset:512
	global_load_dwordx2 v[162:163], v[82:83], off offset:1024
	global_load_dwordx2 v[164:165], v[82:83], off offset:1536
	v_lshl_add_u64 v[82:83], v[82:83], 0, s[22:23]
	global_load_dwordx2 v[166:167], v[82:83], off
	global_load_dwordx2 v[168:169], v[82:83], off offset:512
	global_load_dwordx2 v[170:171], v[82:83], off offset:1024
	global_load_dwordx2 v[172:173], v[82:83], off offset:1536
	s_lshl_b64 s[26:27], s[28:29], 1
	s_add_u32 s26, s38, s26
	v_lshlrev_b64 v[102:103], 10, v[102:103]
	s_addc_u32 s27, s39, s27
	v_lshlrev_b64 v[84:85], 1, v[188:189]
	v_lshl_add_u64 v[102:103], s[26:27], 0, v[102:103]
	v_lshl_add_u64 v[102:103], v[102:103], 0, v[84:85]
	s_waitcnt vmcnt(15)
	v_lshlrev_b32_e32 v182, 16, v142
	v_and_b32_e32 v183, 0xffff0000, v142
	v_lshlrev_b32_e32 v184, 16, v143
	v_and_b32_e32 v185, 0xffff0000, v143
	v_pk_fma_f32 v[194:195], v[174:175], v[182:183], v[50:51]
	v_pk_fma_f32 v[196:197], v[176:177], v[184:185], v[52:53]
	v_mul_f32_e32 v190, 0x3d372713, v194
	v_mul_f32_e32 v191, 0x3d372713, v195
	v_mul_f32_e32 v192, 0x3d372713, v196
	v_mul_f32_e32 v193, 0x3d372713, v197
	v_mul_f32_e32 v190, v194, v190
	v_mul_f32_e32 v191, v195, v191
	v_mul_f32_e32 v192, v196, v192
	v_mul_f32_e32 v193, v197, v193
	v_fma_f32 v190, v194, v190, v194
	v_fma_f32 v191, v195, v191, v195
	v_fma_f32 v192, v196, v192, v196
	v_fma_f32 v193, v197, v193, v197
	v_mul_f32_e32 v190, 0x3f4c422a, v190
	v_mul_f32_e32 v191, 0x3f4c422a, v191
	v_mul_f32_e32 v192, 0x3f4c422a, v192
	v_mul_f32_e32 v193, 0x3f4c422a, v193
	v_mul_f32_e32 v190, 0xc038aa3b, v190
	v_mul_f32_e32 v191, 0xc038aa3b, v191
	v_mul_f32_e32 v192, 0xc038aa3b, v192
	v_mul_f32_e32 v193, 0xc038aa3b, v193
	v_exp_f32_e32 v190, v190
	v_exp_f32_e32 v191, v191
	v_exp_f32_e32 v192, v192
	v_exp_f32_e32 v193, v193
	v_add_f32_e32 v190, 1.0, v190
	v_add_f32_e32 v191, 1.0, v191
	v_add_f32_e32 v192, 1.0, v192
	v_add_f32_e32 v193, 1.0, v193
	v_rcp_f32_e32 v190, v190
	v_rcp_f32_e32 v191, v191
	v_rcp_f32_e32 v192, v192
	v_rcp_f32_e32 v193, v193
	v_pk_mul_f32 v[194:195], v[194:195], v[190:191]
	v_pk_mul_f32 v[196:197], v[196:197], v[192:193]
	v_cvt_pk_bf16_f32 v194, v194, v195
	v_cvt_pk_bf16_f32 v195, v196, v197
	global_store_dwordx2 v[102:103], v[194:195], off
	s_waitcnt vmcnt(15)
	v_lshlrev_b32_e32 v182, 16, v144
	v_and_b32_e32 v183, 0xffff0000, v144
	v_lshlrev_b32_e32 v184, 16, v145
	v_and_b32_e32 v185, 0xffff0000, v145
	v_pk_fma_f32 v[194:195], v[178:179], v[182:183], v[54:55]
	v_pk_fma_f32 v[196:197], v[180:181], v[184:185], v[56:57]
	v_mul_f32_e32 v190, 0x3d372713, v194
	v_mul_f32_e32 v191, 0x3d372713, v195
	v_mul_f32_e32 v192, 0x3d372713, v196
	v_mul_f32_e32 v193, 0x3d372713, v197
	v_mul_f32_e32 v190, v194, v190
	v_mul_f32_e32 v191, v195, v191
	v_mul_f32_e32 v192, v196, v192
	v_mul_f32_e32 v193, v197, v193
	v_fma_f32 v190, v194, v190, v194
	v_fma_f32 v191, v195, v191, v195
	v_fma_f32 v192, v196, v192, v196
	v_fma_f32 v193, v197, v193, v197
	v_mul_f32_e32 v190, 0x3f4c422a, v190
	v_mul_f32_e32 v191, 0x3f4c422a, v191
	v_mul_f32_e32 v192, 0x3f4c422a, v192
	v_mul_f32_e32 v193, 0x3f4c422a, v193
	v_mul_f32_e32 v190, 0xc038aa3b, v190
	v_mul_f32_e32 v191, 0xc038aa3b, v191
	v_mul_f32_e32 v192, 0xc038aa3b, v192
	v_mul_f32_e32 v193, 0xc038aa3b, v193
	v_exp_f32_e32 v190, v190
	v_exp_f32_e32 v191, v191
	v_exp_f32_e32 v192, v192
	v_exp_f32_e32 v193, v193
	v_add_f32_e32 v190, 1.0, v190
	v_add_f32_e32 v191, 1.0, v191
	v_add_f32_e32 v192, 1.0, v192
	v_add_f32_e32 v193, 1.0, v193
	v_rcp_f32_e32 v190, v190
	v_rcp_f32_e32 v191, v191
	v_rcp_f32_e32 v192, v192
	v_rcp_f32_e32 v193, v193
	v_pk_mul_f32 v[194:195], v[194:195], v[190:191]
	v_pk_mul_f32 v[196:197], v[196:197], v[192:193]
	v_cvt_pk_bf16_f32 v194, v194, v195
	v_cvt_pk_bf16_f32 v195, v196, v197
	global_store_dwordx2 v[102:103], v[194:195], off offset:16
	s_waitcnt vmcnt(15)
; #define GAS __attribute__((address_space(1)))
; __device__ __forceinline__ unsigned pk2(float lo, float hi) { const f32x2cv v = {lo, hi}; return __builtin_bit_cast(unsigned, __builtin_convertvector(v, bf16x2cv)); }
; __device__ __forceinline__ float gelu_tanh(float x) { const float u = 0.7978845608028654f * (x + 0.044715f * x * x * x); return x * __builtin_amdgcn_rcpf(1.0f + __builtin_amdgcn_exp2f(-2.8853900817779268f * u)); }
; __device__ __forceinline__ void ph_s5_out(Frame& F) {
;     ...
;                 for (int k = 0; k < 4; ++k) { const int tloc = 2 * (wave + 8 * i) + (k >> 1), p0 = 8 * (k & 1) + 4 * hh; const size_t m = (size_t)chunk * 64 + tloc;
;                     const v2u uw = *(const GAS v2u*)((chunk < 256 ? (const bf16*)(ws + WS_UG) : (const bf16*)(ws + WS_UGC)) + ug_index(g, (int)m, p0));
;                     const float y0 = gelu_tanh(acc[i][4 * k] + dsk[p0] * bflo(uw.x)), y1 = gelu_tanh(acc[i][4 * k + 1] + dsk[p0 + 1] * bfhi(uw.x));
;                     const float y2 = gelu_tanh(acc[i][4 * k + 2] + dsk[p0 + 2] * bflo(uw.y)), y3 = gelu_tanh(acc[i][4 * k + 3] + dsk[p0 + 3] * bfhi(uw.y));
;                     v2u zw; zw.x = pk2(y0, y1); zw.y = pk2(y2, y3);
;                     *(GAS v2u*)((bf16*)(ws + WS_Z) + m * 512 + 16 * g + p0) = zw; }
	v_lshlrev_b32_e32 v182, 16, v146
	v_and_b32_e32 v183, 0xffff0000, v146
	v_lshlrev_b32_e32 v184, 16, v147
	v_and_b32_e32 v185, 0xffff0000, v147
	v_pk_fma_f32 v[194:195], v[174:175], v[182:183], v[58:59]
	v_pk_fma_f32 v[196:197], v[176:177], v[184:185], v[60:61]
	v_mul_f32_e32 v190, 0x3d372713, v194
	v_mul_f32_e32 v191, 0x3d372713, v195
	v_mul_f32_e32 v192, 0x3d372713, v196
	v_mul_f32_e32 v193, 0x3d372713, v197
	v_mul_f32_e32 v190, v194, v190
	v_mul_f32_e32 v191, v195, v191
	v_mul_f32_e32 v192, v196, v192
	v_mul_f32_e32 v193, v197, v193
	v_fma_f32 v190, v194, v190, v194
	v_fma_f32 v191, v195, v191, v195
	v_fma_f32 v192, v196, v192, v196
	v_fma_f32 v193, v197, v193, v197
	v_mul_f32_e32 v190, 0x3f4c422a, v190
	v_mul_f32_e32 v191, 0x3f4c422a, v191
	v_mul_f32_e32 v192, 0x3f4c422a, v192
	v_mul_f32_e32 v193, 0x3f4c422a, v193
	v_mul_f32_e32 v190, 0xc038aa3b, v190
	v_mul_f32_e32 v191, 0xc038aa3b, v191
	v_mul_f32_e32 v192, 0xc038aa3b, v192
	v_mul_f32_e32 v193, 0xc038aa3b, v193
	v_exp_f32_e32 v190, v190
	v_exp_f32_e32 v191, v191
	v_exp_f32_e32 v192, v192
	v_exp_f32_e32 v193, v193
	v_add_f32_e32 v190, 1.0, v190
	v_add_f32_e32 v191, 1.0, v191
	v_add_f32_e32 v192, 1.0, v192
	v_add_f32_e32 v193, 1.0, v193
	v_rcp_f32_e32 v190, v190
	v_rcp_f32_e32 v191, v191
	v_rcp_f32_e32 v192, v192
	v_rcp_f32_e32 v193, v193
	v_pk_mul_f32 v[194:195], v[194:195], v[190:191]
	v_pk_mul_f32 v[196:197], v[196:197], v[192:193]
	v_cvt_pk_bf16_f32 v194, v194, v195
	v_cvt_pk_bf16_f32 v195, v196, v197
	global_store_dwordx2 v[102:103], v[194:195], off offset:1024
	s_waitcnt vmcnt(15)
	v_lshlrev_b32_e32 v182, 16, v148
	v_and_b32_e32 v183, 0xffff0000, v148
	v_lshlrev_b32_e32 v184, 16, v149
	v_and_b32_e32 v185, 0xffff0000, v149
	v_pk_fma_f32 v[194:195], v[178:179], v[182:183], v[62:63]
	v_pk_fma_f32 v[196:197], v[180:181], v[184:185], v[64:65]
	v_mul_f32_e32 v190, 0x3d372713, v194
	v_mul_f32_e32 v191, 0x3d372713, v195
	v_mul_f32_e32 v192, 0x3d372713, v196
	v_mul_f32_e32 v193, 0x3d372713, v197
	v_mul_f32_e32 v190, v194, v190
	v_mul_f32_e32 v191, v195, v191
	v_mul_f32_e32 v192, v196, v192
	v_mul_f32_e32 v193, v197, v193
	v_fma_f32 v190, v194, v190, v194
	v_fma_f32 v191, v195, v191, v195
	v_fma_f32 v192, v196, v192, v196
	v_fma_f32 v193, v197, v193, v197
	v_mul_f32_e32 v190, 0x3f4c422a, v190
	v_mul_f32_e32 v191, 0x3f4c422a, v191
	v_mul_f32_e32 v192, 0x3f4c422a, v192
	v_mul_f32_e32 v193, 0x3f4c422a, v193
	v_mul_f32_e32 v190, 0xc038aa3b, v190
	v_mul_f32_e32 v191, 0xc038aa3b, v191
	v_mul_f32_e32 v192, 0xc038aa3b, v192
	v_mul_f32_e32 v193, 0xc038aa3b, v193
	v_exp_f32_e32 v190, v190
	v_exp_f32_e32 v191, v191
	v_exp_f32_e32 v192, v192
	v_exp_f32_e32 v193, v193
	v_add_f32_e32 v190, 1.0, v190
	v_add_f32_e32 v191, 1.0, v191
	v_add_f32_e32 v192, 1.0, v192
	v_add_f32_e32 v193, 1.0, v193
	v_rcp_f32_e32 v190, v190
	v_rcp_f32_e32 v191, v191
	v_rcp_f32_e32 v192, v192
	v_rcp_f32_e32 v193, v193
	v_pk_mul_f32 v[194:195], v[194:195], v[190:191]
	v_pk_mul_f32 v[196:197], v[196:197], v[192:193]
	v_cvt_pk_bf16_f32 v194, v194, v195
	v_cvt_pk_bf16_f32 v195, v196, v197
	global_store_dwordx2 v[102:103], v[194:195], off offset:1040
	v_lshl_add_u64 v[102:103], v[102:103], 0, s[22:23]
	s_waitcnt vmcnt(15)
	v_lshlrev_b32_e32 v182, 16, v150
	v_and_b32_e32 v183, 0xffff0000, v150
	v_lshlrev_b32_e32 v184, 16, v151
	v_and_b32_e32 v185, 0xffff0000, v151
	v_pk_fma_f32 v[194:195], v[174:175], v[182:183], v[34:35]
	v_pk_fma_f32 v[196:197], v[176:177], v[184:185], v[36:37]
	v_mul_f32_e32 v190, 0x3d372713, v194
	v_mul_f32_e32 v191, 0x3d372713, v195
	v_mul_f32_e32 v192, 0x3d372713, v196
	v_mul_f32_e32 v193, 0x3d372713, v197
	v_mul_f32_e32 v190, v194, v190
	v_mul_f32_e32 v191, v195, v191
	v_mul_f32_e32 v192, v196, v192
	v_mul_f32_e32 v193, v197, v193
	v_fma_f32 v190, v194, v190, v194
	v_fma_f32 v191, v195, v191, v195
	v_fma_f32 v192, v196, v192, v196
	v_fma_f32 v193, v197, v193, v197
	v_mul_f32_e32 v190, 0x3f4c422a, v190
	v_mul_f32_e32 v191, 0x3f4c422a, v191
	v_mul_f32_e32 v192, 0x3f4c422a, v192
	v_mul_f32_e32 v193, 0x3f4c422a, v193
	v_mul_f32_e32 v190, 0xc038aa3b, v190
	v_mul_f32_e32 v191, 0xc038aa3b, v191
	v_mul_f32_e32 v192, 0xc038aa3b, v192
	v_mul_f32_e32 v193, 0xc038aa3b, v193
	v_exp_f32_e32 v190, v190
	v_exp_f32_e32 v191, v191
	v_exp_f32_e32 v192, v192
	v_exp_f32_e32 v193, v193
	v_add_f32_e32 v190, 1.0, v190
	v_add_f32_e32 v191, 1.0, v191
	v_add_f32_e32 v192, 1.0, v192
	v_add_f32_e32 v193, 1.0, v193
	v_rcp_f32_e32 v190, v190
	v_rcp_f32_e32 v191, v191
	v_rcp_f32_e32 v192, v192
	v_rcp_f32_e32 v193, v193
	v_pk_mul_f32 v[194:195], v[194:195], v[190:191]
	v_pk_mul_f32 v[196:197], v[196:197], v[192:193]
	v_cvt_pk_bf16_f32 v194, v194, v195
	v_cvt_pk_bf16_f32 v195, v196, v197
	global_store_dwordx2 v[102:103], v[194:195], off
	s_waitcnt vmcnt(15)
	v_lshlrev_b32_e32 v182, 16, v152
	v_and_b32_e32 v183, 0xffff0000, v152
	v_lshlrev_b32_e32 v184, 16, v153
	v_and_b32_e32 v185, 0xffff0000, v153
	v_pk_fma_f32 v[194:195], v[178:179], v[182:183], v[38:39]
	v_pk_fma_f32 v[196:197], v[180:181], v[184:185], v[40:41]
	v_mul_f32_e32 v190, 0x3d372713, v194
	v_mul_f32_e32 v191, 0x3d372713, v195
	v_mul_f32_e32 v192, 0x3d372713, v196
	v_mul_f32_e32 v193, 0x3d372713, v197
	v_mul_f32_e32 v190, v194, v190
	v_mul_f32_e32 v191, v195, v191
	v_mul_f32_e32 v192, v196, v192
	v_mul_f32_e32 v193, v197, v193
	v_fma_f32 v190, v194, v190, v194
	v_fma_f32 v191, v195, v191, v195
	v_fma_f32 v192, v196, v192, v196
	v_fma_f32 v193, v197, v193, v197
	v_mul_f32_e32 v190, 0x3f4c422a, v190
	v_mul_f32_e32 v191, 0x3f4c422a, v191
	v_mul_f32_e32 v192, 0x3f4c422a, v192
	v_mul_f32_e32 v193, 0x3f4c422a, v193
	v_mul_f32_e32 v190, 0xc038aa3b, v190
	v_mul_f32_e32 v191, 0xc038aa3b, v191
	v_mul_f32_e32 v192, 0xc038aa3b, v192
	v_mul_f32_e32 v193, 0xc038aa3b, v193
	v_exp_f32_e32 v190, v190
	v_exp_f32_e32 v191, v191
	v_exp_f32_e32 v192, v192
	v_exp_f32_e32 v193, v193
	v_add_f32_e32 v190, 1.0, v190
	v_add_f32_e32 v191, 1.0, v191
	v_add_f32_e32 v192, 1.0, v192
	v_add_f32_e32 v193, 1.0, v193
	v_rcp_f32_e32 v190, v190
	v_rcp_f32_e32 v191, v191
	v_rcp_f32_e32 v192, v192
	v_rcp_f32_e32 v193, v193
	v_pk_mul_f32 v[194:195], v[194:195], v[190:191]
	v_pk_mul_f32 v[196:197], v[196:197], v[192:193]
	v_cvt_pk_bf16_f32 v194, v194, v195
	v_cvt_pk_bf16_f32 v195, v196, v197
	global_store_dwordx2 v[102:103], v[194:195], off offset:16
	s_waitcnt vmcnt(15)
; #define GAS __attribute__((address_space(1)))
; __device__ __forceinline__ unsigned pk2(float lo, float hi) { const f32x2cv v = {lo, hi}; return __builtin_bit_cast(unsigned, __builtin_convertvector(v, bf16x2cv)); }
; __device__ __forceinline__ float gelu_tanh(float x) { const float u = 0.7978845608028654f * (x + 0.044715f * x * x * x); return x * __builtin_amdgcn_rcpf(1.0f + __builtin_amdgcn_exp2f(-2.8853900817779268f * u)); }
; __device__ __forceinline__ void ph_s5_out(Frame& F) {
;     ...
;                 for (int k = 0; k < 4; ++k) { const int tloc = 2 * (wave + 8 * i) + (k >> 1), p0 = 8 * (k & 1) + 4 * hh; const size_t m = (size_t)chunk * 64 + tloc;
;                     const v2u uw = *(const GAS v2u*)((chunk < 256 ? (const bf16*)(ws + WS_UG) : (const bf16*)(ws + WS_UGC)) + ug_index(g, (int)m, p0));
;                     const float y0 = gelu_tanh(acc[i][4 * k] + dsk[p0] * bflo(uw.x)), y1 = gelu_tanh(acc[i][4 * k + 1] + dsk[p0 + 1] * bfhi(uw.x));
;                     const float y2 = gelu_tanh(acc[i][4 * k + 2] + dsk[p0 + 2] * bflo(uw.y)), y3 = gelu_tanh(acc[i][4 * k + 3] + dsk[p0 + 3] * bfhi(uw.y));
;                     v2u zw; zw.x = pk2(y0, y1); zw.y = pk2(y2, y3);
;                     *(GAS v2u*)((bf16*)(ws + WS_Z) + m * 512 + 16 * g + p0) = zw; }
	v_lshlrev_b32_e32 v182, 16, v154
	v_and_b32_e32 v183, 0xffff0000, v154
	v_lshlrev_b32_e32 v184, 16, v155
	v_and_b32_e32 v185, 0xffff0000, v155
	v_pk_fma_f32 v[194:195], v[174:175], v[182:183], v[42:43]
	v_pk_fma_f32 v[196:197], v[176:177], v[184:185], v[44:45]
	v_mul_f32_e32 v190, 0x3d372713, v194
	v_mul_f32_e32 v191, 0x3d372713, v195
	v_mul_f32_e32 v192, 0x3d372713, v196
	v_mul_f32_e32 v193, 0x3d372713, v197
	v_mul_f32_e32 v190, v194, v190
	v_mul_f32_e32 v191, v195, v191
	v_mul_f32_e32 v192, v196, v192
	v_mul_f32_e32 v193, v197, v193
	v_fma_f32 v190, v194, v190, v194
	v_fma_f32 v191, v195, v191, v195
	v_fma_f32 v192, v196, v192, v196
	v_fma_f32 v193, v197, v193, v197
	v_mul_f32_e32 v190, 0x3f4c422a, v190
	v_mul_f32_e32 v191, 0x3f4c422a, v191
	v_mul_f32_e32 v192, 0x3f4c422a, v192
	v_mul_f32_e32 v193, 0x3f4c422a, v193
	v_mul_f32_e32 v190, 0xc038aa3b, v190
	v_mul_f32_e32 v191, 0xc038aa3b, v191
	v_mul_f32_e32 v192, 0xc038aa3b, v192
	v_mul_f32_e32 v193, 0xc038aa3b, v193
	v_exp_f32_e32 v190, v190
	v_exp_f32_e32 v191, v191
	v_exp_f32_e32 v192, v192
	v_exp_f32_e32 v193, v193
	v_add_f32_e32 v190, 1.0, v190
	v_add_f32_e32 v191, 1.0, v191
	v_add_f32_e32 v192, 1.0, v192
	v_add_f32_e32 v193, 1.0, v193
	v_rcp_f32_e32 v190, v190
	v_rcp_f32_e32 v191, v191
	v_rcp_f32_e32 v192, v192
	v_rcp_f32_e32 v193, v193
	v_pk_mul_f32 v[194:195], v[194:195], v[190:191]
	v_pk_mul_f32 v[196:197], v[196:197], v[192:193]
	v_cvt_pk_bf16_f32 v194, v194, v195
	v_cvt_pk_bf16_f32 v195, v196, v197
	global_store_dwordx2 v[102:103], v[194:195], off offset:1024
	s_waitcnt vmcnt(15)
	v_lshlrev_b32_e32 v182, 16, v156
	v_and_b32_e32 v183, 0xffff0000, v156
	v_lshlrev_b32_e32 v184, 16, v157
	v_and_b32_e32 v185, 0xffff0000, v157
	v_pk_fma_f32 v[194:195], v[178:179], v[182:183], v[46:47]
	v_pk_fma_f32 v[196:197], v[180:181], v[184:185], v[48:49]
	v_mul_f32_e32 v190, 0x3d372713, v194
	v_mul_f32_e32 v191, 0x3d372713, v195
	v_mul_f32_e32 v192, 0x3d372713, v196
	v_mul_f32_e32 v193, 0x3d372713, v197
	v_mul_f32_e32 v190, v194, v190
	v_mul_f32_e32 v191, v195, v191
	v_mul_f32_e32 v192, v196, v192
	v_mul_f32_e32 v193, v197, v193
	v_fma_f32 v190, v194, v190, v194
	v_fma_f32 v191, v195, v191, v195
	v_fma_f32 v192, v196, v192, v196
	v_fma_f32 v193, v197, v193, v197
	v_mul_f32_e32 v190, 0x3f4c422a, v190
	v_mul_f32_e32 v191, 0x3f4c422a, v191
	v_mul_f32_e32 v192, 0x3f4c422a, v192
	v_mul_f32_e32 v193, 0x3f4c422a, v193
	v_mul_f32_e32 v190, 0xc038aa3b, v190
	v_mul_f32_e32 v191, 0xc038aa3b, v191
	v_mul_f32_e32 v192, 0xc038aa3b, v192
	v_mul_f32_e32 v193, 0xc038aa3b, v193
	v_exp_f32_e32 v190, v190
	v_exp_f32_e32 v191, v191
	v_exp_f32_e32 v192, v192
	v_exp_f32_e32 v193, v193
	v_add_f32_e32 v190, 1.0, v190
	v_add_f32_e32 v191, 1.0, v191
	v_add_f32_e32 v192, 1.0, v192
	v_add_f32_e32 v193, 1.0, v193
	v_rcp_f32_e32 v190, v190
	v_rcp_f32_e32 v191, v191
	v_rcp_f32_e32 v192, v192
	v_rcp_f32_e32 v193, v193
	v_pk_mul_f32 v[194:195], v[194:195], v[190:191]
	v_pk_mul_f32 v[196:197], v[196:197], v[192:193]
	v_cvt_pk_bf16_f32 v194, v194, v195
	v_cvt_pk_bf16_f32 v195, v196, v197
	global_store_dwordx2 v[102:103], v[194:195], off offset:1040
	v_lshl_add_u64 v[102:103], v[102:103], 0, s[22:23]
	s_waitcnt vmcnt(15)
	v_lshlrev_b32_e32 v182, 16, v158
	v_and_b32_e32 v183, 0xffff0000, v158
	v_lshlrev_b32_e32 v184, 16, v159
	v_and_b32_e32 v185, 0xffff0000, v159
	v_pk_fma_f32 v[194:195], v[174:175], v[182:183], v[18:19]
	v_pk_fma_f32 v[196:197], v[176:177], v[184:185], v[20:21]
	v_mul_f32_e32 v190, 0x3d372713, v194
	v_mul_f32_e32 v191, 0x3d372713, v195
	v_mul_f32_e32 v192, 0x3d372713, v196
	v_mul_f32_e32 v193, 0x3d372713, v197
	v_mul_f32_e32 v190, v194, v190
	v_mul_f32_e32 v191, v195, v191
	v_mul_f32_e32 v192, v196, v192
	v_mul_f32_e32 v193, v197, v193
	v_fma_f32 v190, v194, v190, v194
	v_fma_f32 v191, v195, v191, v195
	v_fma_f32 v192, v196, v192, v196
	v_fma_f32 v193, v197, v193, v197
	v_mul_f32_e32 v190, 0x3f4c422a, v190
	v_mul_f32_e32 v191, 0x3f4c422a, v191
	v_mul_f32_e32 v192, 0x3f4c422a, v192
	v_mul_f32_e32 v193, 0x3f4c422a, v193
	v_mul_f32_e32 v190, 0xc038aa3b, v190
	v_mul_f32_e32 v191, 0xc038aa3b, v191
	v_mul_f32_e32 v192, 0xc038aa3b, v192
	v_mul_f32_e32 v193, 0xc038aa3b, v193
	v_exp_f32_e32 v190, v190
	v_exp_f32_e32 v191, v191
	v_exp_f32_e32 v192, v192
	v_exp_f32_e32 v193, v193
	v_add_f32_e32 v190, 1.0, v190
	v_add_f32_e32 v191, 1.0, v191
	v_add_f32_e32 v192, 1.0, v192
	v_add_f32_e32 v193, 1.0, v193
	v_rcp_f32_e32 v190, v190
	v_rcp_f32_e32 v191, v191
	v_rcp_f32_e32 v192, v192
	v_rcp_f32_e32 v193, v193
	v_pk_mul_f32 v[194:195], v[194:195], v[190:191]
	v_pk_mul_f32 v[196:197], v[196:197], v[192:193]
	v_cvt_pk_bf16_f32 v194, v194, v195
	v_cvt_pk_bf16_f32 v195, v196, v197
	global_store_dwordx2 v[102:103], v[194:195], off
	s_waitcnt vmcnt(15)
	v_lshlrev_b32_e32 v182, 16, v160
	v_and_b32_e32 v183, 0xffff0000, v160
	v_lshlrev_b32_e32 v184, 16, v161
	v_and_b32_e32 v185, 0xffff0000, v161
	v_pk_fma_f32 v[194:195], v[178:179], v[182:183], v[22:23]
	v_pk_fma_f32 v[196:197], v[180:181], v[184:185], v[24:25]
	v_mul_f32_e32 v190, 0x3d372713, v194
	v_mul_f32_e32 v191, 0x3d372713, v195
	v_mul_f32_e32 v192, 0x3d372713, v196
	v_mul_f32_e32 v193, 0x3d372713, v197
	v_mul_f32_e32 v190, v194, v190
	v_mul_f32_e32 v191, v195, v191
	v_mul_f32_e32 v192, v196, v192
	v_mul_f32_e32 v193, v197, v193
	v_fma_f32 v190, v194, v190, v194
	v_fma_f32 v191, v195, v191, v195
	v_fma_f32 v192, v196, v192, v196
	v_fma_f32 v193, v197, v193, v197
	v_mul_f32_e32 v190, 0x3f4c422a, v190
	v_mul_f32_e32 v191, 0x3f4c422a, v191
	v_mul_f32_e32 v192, 0x3f4c422a, v192
	v_mul_f32_e32 v193, 0x3f4c422a, v193
	v_mul_f32_e32 v190, 0xc038aa3b, v190
	v_mul_f32_e32 v191, 0xc038aa3b, v191
	v_mul_f32_e32 v192, 0xc038aa3b, v192
	v_mul_f32_e32 v193, 0xc038aa3b, v193
	v_exp_f32_e32 v190, v190
	v_exp_f32_e32 v191, v191
	v_exp_f32_e32 v192, v192
	v_exp_f32_e32 v193, v193
	v_add_f32_e32 v190, 1.0, v190
	v_add_f32_e32 v191, 1.0, v191
	v_add_f32_e32 v192, 1.0, v192
	v_add_f32_e32 v193, 1.0, v193
	v_rcp_f32_e32 v190, v190
	v_rcp_f32_e32 v191, v191
	v_rcp_f32_e32 v192, v192
	v_rcp_f32_e32 v193, v193
	v_pk_mul_f32 v[194:195], v[194:195], v[190:191]
	v_pk_mul_f32 v[196:197], v[196:197], v[192:193]
	v_cvt_pk_bf16_f32 v194, v194, v195
	v_cvt_pk_bf16_f32 v195, v196, v197
	global_store_dwordx2 v[102:103], v[194:195], off offset:16
	s_waitcnt vmcnt(15)
; #define GAS __attribute__((address_space(1)))
; __device__ __forceinline__ unsigned pk2(float lo, float hi) { const f32x2cv v = {lo, hi}; return __builtin_bit_cast(unsigned, __builtin_convertvector(v, bf16x2cv)); }
; __device__ __forceinline__ float gelu_tanh(float x) { const float u = 0.7978845608028654f * (x + 0.044715f * x * x * x); return x * __builtin_amdgcn_rcpf(1.0f + __builtin_amdgcn_exp2f(-2.8853900817779268f * u)); }
; __device__ __forceinline__ void ph_s5_out(Frame& F) {
;     ...
;                 for (int k = 0; k < 4; ++k) { const int tloc = 2 * (wave + 8 * i) + (k >> 1), p0 = 8 * (k & 1) + 4 * hh; const size_t m = (size_t)chunk * 64 + tloc;
;                     const v2u uw = *(const GAS v2u*)((chunk < 256 ? (const bf16*)(ws + WS_UG) : (const bf16*)(ws + WS_UGC)) + ug_index(g, (int)m, p0));
;                     const float y0 = gelu_tanh(acc[i][4 * k] + dsk[p0] * bflo(uw.x)), y1 = gelu_tanh(acc[i][4 * k + 1] + dsk[p0 + 1] * bfhi(uw.x));
;                     const float y2 = gelu_tanh(acc[i][4 * k + 2] + dsk[p0 + 2] * bflo(uw.y)), y3 = gelu_tanh(acc[i][4 * k + 3] + dsk[p0 + 3] * bfhi(uw.y));
;                     v2u zw; zw.x = pk2(y0, y1); zw.y = pk2(y2, y3);
;                     *(GAS v2u*)((bf16*)(ws + WS_Z) + m * 512 + 16 * g + p0) = zw; }
	v_lshlrev_b32_e32 v182, 16, v162
	v_and_b32_e32 v183, 0xffff0000, v162
	v_lshlrev_b32_e32 v184, 16, v163
	v_and_b32_e32 v185, 0xffff0000, v163
	v_pk_fma_f32 v[194:195], v[174:175], v[182:183], v[26:27]
	v_pk_fma_f32 v[196:197], v[176:177], v[184:185], v[28:29]
	v_mul_f32_e32 v190, 0x3d372713, v194
	v_mul_f32_e32 v191, 0x3d372713, v195
	v_mul_f32_e32 v192, 0x3d372713, v196
	v_mul_f32_e32 v193, 0x3d372713, v197
	v_mul_f32_e32 v190, v194, v190
	v_mul_f32_e32 v191, v195, v191
	v_mul_f32_e32 v192, v196, v192
	v_mul_f32_e32 v193, v197, v193
	v_fma_f32 v190, v194, v190, v194
	v_fma_f32 v191, v195, v191, v195
	v_fma_f32 v192, v196, v192, v196
	v_fma_f32 v193, v197, v193, v197
	v_mul_f32_e32 v190, 0x3f4c422a, v190
	v_mul_f32_e32 v191, 0x3f4c422a, v191
	v_mul_f32_e32 v192, 0x3f4c422a, v192
	v_mul_f32_e32 v193, 0x3f4c422a, v193
	v_mul_f32_e32 v190, 0xc038aa3b, v190
	v_mul_f32_e32 v191, 0xc038aa3b, v191
	v_mul_f32_e32 v192, 0xc038aa3b, v192
	v_mul_f32_e32 v193, 0xc038aa3b, v193
	v_exp_f32_e32 v190, v190
	v_exp_f32_e32 v191, v191
	v_exp_f32_e32 v192, v192
	v_exp_f32_e32 v193, v193
	v_add_f32_e32 v190, 1.0, v190
	v_add_f32_e32 v191, 1.0, v191
	v_add_f32_e32 v192, 1.0, v192
	v_add_f32_e32 v193, 1.0, v193
	v_rcp_f32_e32 v190, v190
	v_rcp_f32_e32 v191, v191
	v_rcp_f32_e32 v192, v192
	v_rcp_f32_e32 v193, v193
	v_pk_mul_f32 v[194:195], v[194:195], v[190:191]
	v_pk_mul_f32 v[196:197], v[196:197], v[192:193]
	v_cvt_pk_bf16_f32 v194, v194, v195
	v_cvt_pk_bf16_f32 v195, v196, v197
	global_store_dwordx2 v[102:103], v[194:195], off offset:1024
	s_waitcnt vmcnt(15)
	v_lshlrev_b32_e32 v182, 16, v164
	v_and_b32_e32 v183, 0xffff0000, v164
	v_lshlrev_b32_e32 v184, 16, v165
	v_and_b32_e32 v185, 0xffff0000, v165
	v_pk_fma_f32 v[194:195], v[178:179], v[182:183], v[30:31]
	v_pk_fma_f32 v[196:197], v[180:181], v[184:185], v[32:33]
	v_mul_f32_e32 v190, 0x3d372713, v194
	v_mul_f32_e32 v191, 0x3d372713, v195
	v_mul_f32_e32 v192, 0x3d372713, v196
	v_mul_f32_e32 v193, 0x3d372713, v197
	v_mul_f32_e32 v190, v194, v190
	v_mul_f32_e32 v191, v195, v191
	v_mul_f32_e32 v192, v196, v192
	v_mul_f32_e32 v193, v197, v193
	v_fma_f32 v190, v194, v190, v194
	v_fma_f32 v191, v195, v191, v195
	v_fma_f32 v192, v196, v192, v196
	v_fma_f32 v193, v197, v193, v197
	v_mul_f32_e32 v190, 0x3f4c422a, v190
	v_mul_f32_e32 v191, 0x3f4c422a, v191
	v_mul_f32_e32 v192, 0x3f4c422a, v192
	v_mul_f32_e32 v193, 0x3f4c422a, v193
	v_mul_f32_e32 v190, 0xc038aa3b, v190
	v_mul_f32_e32 v191, 0xc038aa3b, v191
	v_mul_f32_e32 v192, 0xc038aa3b, v192
	v_mul_f32_e32 v193, 0xc038aa3b, v193
	v_exp_f32_e32 v190, v190
	v_exp_f32_e32 v191, v191
	v_exp_f32_e32 v192, v192
	v_exp_f32_e32 v193, v193
	v_add_f32_e32 v190, 1.0, v190
	v_add_f32_e32 v191, 1.0, v191
	v_add_f32_e32 v192, 1.0, v192
	v_add_f32_e32 v193, 1.0, v193
	v_rcp_f32_e32 v190, v190
	v_rcp_f32_e32 v191, v191
	v_rcp_f32_e32 v192, v192
	v_rcp_f32_e32 v193, v193
	v_pk_mul_f32 v[194:195], v[194:195], v[190:191]
	v_pk_mul_f32 v[196:197], v[196:197], v[192:193]
	v_cvt_pk_bf16_f32 v194, v194, v195
	v_cvt_pk_bf16_f32 v195, v196, v197
	global_store_dwordx2 v[102:103], v[194:195], off offset:1040
	v_lshl_add_u64 v[102:103], v[102:103], 0, s[22:23]
	s_waitcnt vmcnt(15)
	v_lshlrev_b32_e32 v182, 16, v166
	v_and_b32_e32 v183, 0xffff0000, v166
	v_lshlrev_b32_e32 v184, 16, v167
	v_and_b32_e32 v185, 0xffff0000, v167
	v_pk_fma_f32 v[194:195], v[174:175], v[182:183], v[2:3]
	v_pk_fma_f32 v[196:197], v[176:177], v[184:185], v[4:5]
	v_mul_f32_e32 v190, 0x3d372713, v194
	v_mul_f32_e32 v191, 0x3d372713, v195
	v_mul_f32_e32 v192, 0x3d372713, v196
	v_mul_f32_e32 v193, 0x3d372713, v197
	v_mul_f32_e32 v190, v194, v190
	v_mul_f32_e32 v191, v195, v191
	v_mul_f32_e32 v192, v196, v192
	v_mul_f32_e32 v193, v197, v193
	v_fma_f32 v190, v194, v190, v194
	v_fma_f32 v191, v195, v191, v195
	v_fma_f32 v192, v196, v192, v196
	v_fma_f32 v193, v197, v193, v197
	v_mul_f32_e32 v190, 0x3f4c422a, v190
	v_mul_f32_e32 v191, 0x3f4c422a, v191
	v_mul_f32_e32 v192, 0x3f4c422a, v192
	v_mul_f32_e32 v193, 0x3f4c422a, v193
	v_mul_f32_e32 v190, 0xc038aa3b, v190
	v_mul_f32_e32 v191, 0xc038aa3b, v191
	v_mul_f32_e32 v192, 0xc038aa3b, v192
	v_mul_f32_e32 v193, 0xc038aa3b, v193
	v_exp_f32_e32 v190, v190
	v_exp_f32_e32 v191, v191
	v_exp_f32_e32 v192, v192
	v_exp_f32_e32 v193, v193
	v_add_f32_e32 v190, 1.0, v190
	v_add_f32_e32 v191, 1.0, v191
	v_add_f32_e32 v192, 1.0, v192
	v_add_f32_e32 v193, 1.0, v193
	v_rcp_f32_e32 v190, v190
	v_rcp_f32_e32 v191, v191
	v_rcp_f32_e32 v192, v192
	v_rcp_f32_e32 v193, v193
	v_pk_mul_f32 v[194:195], v[194:195], v[190:191]
	v_pk_mul_f32 v[196:197], v[196:197], v[192:193]
	v_cvt_pk_bf16_f32 v194, v194, v195
	v_cvt_pk_bf16_f32 v195, v196, v197
	global_store_dwordx2 v[102:103], v[194:195], off
	s_waitcnt vmcnt(15)
; #define GAS __attribute__((address_space(1)))
; __device__ __forceinline__ unsigned pk2(float lo, float hi) { const f32x2cv v = {lo, hi}; return __builtin_bit_cast(unsigned, __builtin_convertvector(v, bf16x2cv)); }
; __device__ __forceinline__ float gelu_tanh(float x) { const float u = 0.7978845608028654f * (x + 0.044715f * x * x * x); return x * __builtin_amdgcn_rcpf(1.0f + __builtin_amdgcn_exp2f(-2.8853900817779268f * u)); }
; __device__ __forceinline__ void ph_s5_out(Frame& F) {
;     ...
;                 for (int k = 0; k < 4; ++k) { const int tloc = 2 * (wave + 8 * i) + (k >> 1), p0 = 8 * (k & 1) + 4 * hh; const size_t m = (size_t)chunk * 64 + tloc;
;                     const v2u uw = *(const GAS v2u*)((chunk < 256 ? (const bf16*)(ws + WS_UG) : (const bf16*)(ws + WS_UGC)) + ug_index(g, (int)m, p0));
;                     const float y0 = gelu_tanh(acc[i][4 * k] + dsk[p0] * bflo(uw.x)), y1 = gelu_tanh(acc[i][4 * k + 1] + dsk[p0 + 1] * bfhi(uw.x));
;                     const float y2 = gelu_tanh(acc[i][4 * k + 2] + dsk[p0 + 2] * bflo(uw.y)), y3 = gelu_tanh(acc[i][4 * k + 3] + dsk[p0 + 3] * bfhi(uw.y));
;                     v2u zw; zw.x = pk2(y0, y1); zw.y = pk2(y2, y3);
;                     *(GAS v2u*)((bf16*)(ws + WS_Z) + m * 512 + 16 * g + p0) = zw; }
	v_lshlrev_b32_e32 v182, 16, v168
	v_and_b32_e32 v183, 0xffff0000, v168
	v_lshlrev_b32_e32 v184, 16, v169
	v_and_b32_e32 v185, 0xffff0000, v169
	v_pk_fma_f32 v[194:195], v[178:179], v[182:183], v[6:7]
	v_pk_fma_f32 v[196:197], v[180:181], v[184:185], v[8:9]
	v_mul_f32_e32 v190, 0x3d372713, v194
	v_mul_f32_e32 v191, 0x3d372713, v195
	v_mul_f32_e32 v192, 0x3d372713, v196
	v_mul_f32_e32 v193, 0x3d372713, v197
	v_mul_f32_e32 v190, v194, v190
	v_mul_f32_e32 v191, v195, v191
	v_mul_f32_e32 v192, v196, v192
	v_mul_f32_e32 v193, v197, v193
	v_fma_f32 v190, v194, v190, v194
	v_fma_f32 v191, v195, v191, v195
	v_fma_f32 v192, v196, v192, v196
	v_fma_f32 v193, v197, v193, v197
	v_mul_f32_e32 v190, 0x3f4c422a, v190
	v_mul_f32_e32 v191, 0x3f4c422a, v191
	v_mul_f32_e32 v192, 0x3f4c422a, v192
	v_mul_f32_e32 v193, 0x3f4c422a, v193
	v_mul_f32_e32 v190, 0xc038aa3b, v190
	v_mul_f32_e32 v191, 0xc038aa3b, v191
	v_mul_f32_e32 v192, 0xc038aa3b, v192
	v_mul_f32_e32 v193, 0xc038aa3b, v193
	v_exp_f32_e32 v190, v190
	v_exp_f32_e32 v191, v191
	v_exp_f32_e32 v192, v192
	v_exp_f32_e32 v193, v193
	v_add_f32_e32 v190, 1.0, v190
	v_add_f32_e32 v191, 1.0, v191
	v_add_f32_e32 v192, 1.0, v192
	v_add_f32_e32 v193, 1.0, v193
	v_rcp_f32_e32 v190, v190
	v_rcp_f32_e32 v191, v191
	v_rcp_f32_e32 v192, v192
	v_rcp_f32_e32 v193, v193
	v_pk_mul_f32 v[194:195], v[194:195], v[190:191]
	v_pk_mul_f32 v[196:197], v[196:197], v[192:193]
	v_cvt_pk_bf16_f32 v194, v194, v195
	v_cvt_pk_bf16_f32 v195, v196, v197
	global_store_dwordx2 v[102:103], v[194:195], off offset:16
	s_waitcnt vmcnt(15)
	v_lshlrev_b32_e32 v182, 16, v170
	v_and_b32_e32 v183, 0xffff0000, v170
	v_lshlrev_b32_e32 v184, 16, v171
	v_and_b32_e32 v185, 0xffff0000, v171
	v_pk_fma_f32 v[194:195], v[174:175], v[182:183], v[10:11]
	v_pk_fma_f32 v[196:197], v[176:177], v[184:185], v[12:13]
	v_mul_f32_e32 v190, 0x3d372713, v194
	v_mul_f32_e32 v191, 0x3d372713, v195
	v_mul_f32_e32 v192, 0x3d372713, v196
	v_mul_f32_e32 v193, 0x3d372713, v197
	v_mul_f32_e32 v190, v194, v190
	v_mul_f32_e32 v191, v195, v191
	v_mul_f32_e32 v192, v196, v192
	v_mul_f32_e32 v193, v197, v193
	v_fma_f32 v190, v194, v190, v194
	v_fma_f32 v191, v195, v191, v195
	v_fma_f32 v192, v196, v192, v196
	v_fma_f32 v193, v197, v193, v197
	v_mul_f32_e32 v190, 0x3f4c422a, v190
	v_mul_f32_e32 v191, 0x3f4c422a, v191
	v_mul_f32_e32 v192, 0x3f4c422a, v192
	v_mul_f32_e32 v193, 0x3f4c422a, v193
	v_mul_f32_e32 v190, 0xc038aa3b, v190
	v_mul_f32_e32 v191, 0xc038aa3b, v191
	v_mul_f32_e32 v192, 0xc038aa3b, v192
	v_mul_f32_e32 v193, 0xc038aa3b, v193
	v_exp_f32_e32 v190, v190
	v_exp_f32_e32 v191, v191
	v_exp_f32_e32 v192, v192
	v_exp_f32_e32 v193, v193
	v_add_f32_e32 v190, 1.0, v190
	v_add_f32_e32 v191, 1.0, v191
	v_add_f32_e32 v192, 1.0, v192
	v_add_f32_e32 v193, 1.0, v193
	v_rcp_f32_e32 v190, v190
	v_rcp_f32_e32 v191, v191
	v_rcp_f32_e32 v192, v192
	v_rcp_f32_e32 v193, v193
	v_pk_mul_f32 v[194:195], v[194:195], v[190:191]
	v_pk_mul_f32 v[196:197], v[196:197], v[192:193]
	v_cvt_pk_bf16_f32 v194, v194, v195
	v_cvt_pk_bf16_f32 v195, v196, v197
	global_store_dwordx2 v[102:103], v[194:195], off offset:1024
	s_waitcnt vmcnt(15)
	v_lshlrev_b32_e32 v182, 16, v172
	v_and_b32_e32 v183, 0xffff0000, v172
	v_lshlrev_b32_e32 v184, 16, v173
	v_and_b32_e32 v185, 0xffff0000, v173
	v_pk_fma_f32 v[194:195], v[178:179], v[182:183], v[14:15]
	v_pk_fma_f32 v[196:197], v[180:181], v[184:185], v[16:17]
	v_mul_f32_e32 v190, 0x3d372713, v194
	v_mul_f32_e32 v191, 0x3d372713, v195
	v_mul_f32_e32 v192, 0x3d372713, v196
	v_mul_f32_e32 v193, 0x3d372713, v197
	v_mul_f32_e32 v190, v194, v190
	v_mul_f32_e32 v191, v195, v191
	v_mul_f32_e32 v192, v196, v192
	v_mul_f32_e32 v193, v197, v193
	v_fma_f32 v190, v194, v190, v194
	v_fma_f32 v191, v195, v191, v195
	v_fma_f32 v192, v196, v192, v196
	v_fma_f32 v193, v197, v193, v197
	v_mul_f32_e32 v190, 0x3f4c422a, v190
	v_mul_f32_e32 v191, 0x3f4c422a, v191
	v_mul_f32_e32 v192, 0x3f4c422a, v192
	v_mul_f32_e32 v193, 0x3f4c422a, v193
	v_mul_f32_e32 v190, 0xc038aa3b, v190
	v_mul_f32_e32 v191, 0xc038aa3b, v191
	v_mul_f32_e32 v192, 0xc038aa3b, v192
	v_mul_f32_e32 v193, 0xc038aa3b, v193
	v_exp_f32_e32 v190, v190
	v_exp_f32_e32 v191, v191
	v_exp_f32_e32 v192, v192
	v_exp_f32_e32 v193, v193
	v_add_f32_e32 v190, 1.0, v190
	v_add_f32_e32 v191, 1.0, v191
	v_add_f32_e32 v192, 1.0, v192
	v_add_f32_e32 v193, 1.0, v193
	v_rcp_f32_e32 v190, v190
	v_rcp_f32_e32 v191, v191
	v_rcp_f32_e32 v192, v192
	v_rcp_f32_e32 v193, v193
	v_pk_mul_f32 v[194:195], v[194:195], v[190:191]
	v_pk_mul_f32 v[196:197], v[196:197], v[192:193]
	v_cvt_pk_bf16_f32 v194, v194, v195
	v_cvt_pk_bf16_f32 v195, v196, v197
	global_store_dwordx2 v[102:103], v[194:195], off offset:1040
	s_branch .LBB0_963
